# GEMM K-loops: scalar-base LDS-DMA loads in the single-stage segments (4 VALU adds and 2 SALU adds per iteration removed)
# baseline (speedup 1.0000x reference)
; #define PG8_STAGE(bufoff, gbase, voff) do { _Pragma("unroll") for (int _i = 0; _i < 2; ++_i) \
;         __builtin_amdgcn_global_load_lds((const unsigned*)((const char*)(gbase) + (voff)[_i]), (PG8_LAS unsigned*)(lds + (bufoff) + ldsw + _i * 8192), 16, 0, 0); } while (0)
; #define PG8_LDA(dst, b, h) do { _Pragma("unroll") for (int m = 0; m < 4; ++m) _Pragma("unroll") for (int k = 0; k < 2; ++k) dst[m][k] = *(const PG8_LAS bf16x8*)(lds + PG8_SA(b, h) + aoff + m * 2048 + k * 1024); } while (0)
; #define PG8_LDB(dst, b, h) do { _Pragma("unroll") for (int n = 0; n < 2; ++n) _Pragma("unroll") for (int k = 0; k < 2; ++k) dst[n][k] = *(const PG8_LAS bf16x8*)(lds + PG8_SB(b, h) + boff + n * 2048 + k * 1024); } while (0)
; #define PG8_MMA(ai, bj, At, Bt) do { __builtin_amdgcn_s_setprio(1); _Pragma("unroll") for (int m = 0; m < 4; ++m) _Pragma("unroll") for (int n = 0; n < 2; ++n) _Pragma("unroll") for (int k = 0; k < 2; ++k) \
;         acc[ai][bj][m][n] = __builtin_amdgcn_mfma_f32_16x16x32_bf16(Bt[n][k], At[m][k], acc[ai][bj][m][n], 0, 0, 0); __builtin_amdgcn_s_setprio(0); } while (0)
; #define PG8_WAIT_V(n) asm volatile("s_waitcnt vmcnt(" #n ")" ::: "memory")
; #define PG8_WAIT_L(n) asm volatile("s_waitcnt lgkmcnt(" #n ")" ::: "memory")
; #define PG8_BAR __builtin_amdgcn_s_barrier()
; #define PG8_SCHED __builtin_amdgcn_sched_barrier(0)
; template <class Epi, class Sched, bool ALIGN_EPI = false, bool SP2 = false>
; __device__ __forceinline__ void gemm_phase(PG8_LAS unsigned char* lds, const Gemm g, const Sched& S, const Epi& E) {
;     ...
;         for (int t = 0; t < nt; t += 2) {
;             const bool last = (t == nt - 2);
;             const char* a1 = cA + (size_t)(t + 1) * kstep;
;             const char* a2 = last ? nA : cA + (size_t)(t + 2) * kstep; const char* b2 = last ? nB : cB + (size_t)(t + 2) * kstep;
;             const char* a3 = a2 + kstep; const char* b3 = b2 + kstep;
;             if (last && has_next) S.a_ready(nxt);
;             if constexpr (SP2) {
;             PG8_LDB(B0, 0, 0); PG8_LDB(B1, 0, 1); PG8_SCHED; PG8_LDA(At, 0, 0); PG8_STAGE(PG8_SA(1, 1), a1 + hstep, voffA);
;             PG8_WAIT_V(8); PG8_WAIT_L(0); PG8_BAR; PG8_MMA(0, 0, At, B0); PG8_MMA(0, 1, At, B1); PG8_BAR; PG8_SCHED;
;             PG8_LDA(At, 0, 1); PG8_STAGE(PG8_SB(0, 0), b2, voffB); PG8_STAGE(PG8_SB(0, 1), b2 + hstep, voffB); PG8_STAGE(PG8_SA(0, 0), a2, voffA);
.LBB0_341:
	s_add_i32 s44, s20, 2
	s_add_u32 s45, s16, 0x80
	s_addc_u32 s21, s17, 0
	s_cmp_eq_u32 s70, s20
	s_cselect_b32 s21, s7, s21
	s_cselect_b32 s20, s6, s45
	s_cselect_b32 s47, s57, s39
	s_cselect_b32 s46, s56, s33
	ds_read_b128 v[82:85], v167
	ds_read_b128 v[86:89], v167 offset:1024
	ds_read_b128 v[138:141], v167 offset:2048
	ds_read_b128 v[142:145], v167 offset:3072
	ds_read_b128 v[158:161], v167 offset:16384
	ds_read_b128 v[162:165], v167 offset:17408
	ds_read_b128 v[170:173], v167 offset:18432
	ds_read_b128 v[174:177], v167 offset:19456
	s_add_i32 m0, s63, 0xc000
	ds_read_b128 v[178:181], v169
	ds_read_b128 v[182:185], v169 offset:1024
	ds_read_b128 v[186:189], v169 offset:2048
	ds_read_b128 v[190:193], v169 offset:3072
	ds_read_b128 v[194:197], v169 offset:4096
	ds_read_b128 v[198:201], v169 offset:5120
	ds_read_b128 v[202:205], v169 offset:6144
	global_load_lds_dwordx4 v154, s[16:17]
	s_add_i32 m0, s63, 0xe000
	ds_read_b128 v[206:209], v169 offset:7168
	global_load_lds_dwordx4 v156, s[16:17]
	s_waitcnt vmcnt(8)
	s_waitcnt lgkmcnt(0)
	s_barrier
	s_setprio 1
	v_mfma_f32_16x16x32_bf16 v[134:137], v[82:85], v[178:181], v[134:137]
	v_mfma_f32_16x16x32_bf16 v[130:133], v[138:141], v[178:181], v[130:133]
	v_mfma_f32_16x16x32_bf16 v[126:129], v[82:85], v[186:189], v[126:129]
	v_mfma_f32_16x16x32_bf16 v[122:125], v[138:141], v[186:189], v[122:125]
	v_mfma_f32_16x16x32_bf16 v[118:121], v[82:85], v[194:197], v[118:121]
	v_mfma_f32_16x16x32_bf16 v[114:117], v[138:141], v[194:197], v[114:117]
	v_mfma_f32_16x16x32_bf16 v[110:113], v[82:85], v[202:205], v[110:113]
	v_mfma_f32_16x16x32_bf16 v[106:109], v[138:141], v[202:205], v[106:109]
	v_mfma_f32_16x16x32_bf16 v[134:137], v[86:89], v[182:185], v[134:137]
	v_mfma_f32_16x16x32_bf16 v[130:133], v[142:145], v[182:185], v[130:133]
	v_mfma_f32_16x16x32_bf16 v[126:129], v[86:89], v[190:193], v[126:129]
	v_mfma_f32_16x16x32_bf16 v[122:125], v[142:145], v[190:193], v[122:125]
	v_mfma_f32_16x16x32_bf16 v[118:121], v[86:89], v[198:201], v[118:121]
	v_mfma_f32_16x16x32_bf16 v[114:117], v[142:145], v[198:201], v[114:117]
	v_mfma_f32_16x16x32_bf16 v[110:113], v[86:89], v[206:209], v[110:113]
	v_mfma_f32_16x16x32_bf16 v[106:109], v[142:145], v[206:209], v[106:109]
	v_mfma_f32_16x16x32_bf16 v[62:65], v[158:161], v[178:181], v[62:65]
	v_mfma_f32_16x16x32_bf16 v[58:61], v[170:173], v[178:181], v[58:61]
	v_mfma_f32_16x16x32_bf16 v[54:57], v[158:161], v[186:189], v[54:57]
	v_mfma_f32_16x16x32_bf16 v[50:53], v[170:173], v[186:189], v[50:53]
	v_mfma_f32_16x16x32_bf16 v[46:49], v[158:161], v[194:197], v[46:49]
	v_mfma_f32_16x16x32_bf16 v[42:45], v[170:173], v[194:197], v[42:45]
	v_mfma_f32_16x16x32_bf16 v[38:41], v[158:161], v[202:205], v[38:41]
	v_mfma_f32_16x16x32_bf16 v[34:37], v[170:173], v[202:205], v[34:37]
	v_mfma_f32_16x16x32_bf16 v[62:65], v[162:165], v[182:185], v[62:65]
	v_mfma_f32_16x16x32_bf16 v[58:61], v[174:177], v[182:185], v[58:61]
	v_mfma_f32_16x16x32_bf16 v[54:57], v[162:165], v[190:193], v[54:57]
	v_mfma_f32_16x16x32_bf16 v[50:53], v[174:177], v[190:193], v[50:53]
	v_mfma_f32_16x16x32_bf16 v[46:49], v[162:165], v[198:201], v[46:49]
	v_mfma_f32_16x16x32_bf16 v[42:45], v[174:177], v[198:201], v[42:45]
	v_mfma_f32_16x16x32_bf16 v[38:41], v[162:165], v[206:209], v[38:41]
	v_mfma_f32_16x16x32_bf16 v[34:37], v[174:177], v[206:209], v[34:37]
	s_setprio 0
	s_barrier
	v_lshl_add_u64 v[210:211], s[46:47], 0, v[148:149]
	s_add_i32 m0, s62, 0x10000
	ds_read_b128 v[178:181], v169 offset:16384
	ds_read_b128 v[182:185], v169 offset:17408
	ds_read_b128 v[186:189], v169 offset:18432
	ds_read_b128 v[190:193], v169 offset:19456
	ds_read_b128 v[194:197], v169 offset:20480
	ds_read_b128 v[198:201], v169 offset:21504
	ds_read_b128 v[202:205], v169 offset:22528
	ds_read_b128 v[206:209], v169 offset:23552
	global_load_lds_dwordx4 v[210:211], off
	s_add_i32 m0, s62, 0x12000
	v_lshl_add_u64 v[212:213], s[46:47], 0, v[152:153]
	s_add_u32 s46, s46, s10
	s_addc_u32 s47, s47, s11
	global_load_lds_dwordx4 v[212:213], off
	v_lshl_add_u64 v[214:215], s[46:47], 0, v[148:149]
	s_add_i32 m0, s62, 0x14000
	v_lshl_add_u64 v[218:219], s[46:47], 0, v[152:153]
	global_load_lds_dwordx4 v[214:215], off
	s_add_i32 m0, s62, 0x16000
	v_lshl_add_u64 v[220:221], s[20:21], 0, v[146:147]
	global_load_lds_dwordx4 v[218:219], off
	s_mov_b32 m0, s63
	v_lshl_add_u64 v[222:223], s[20:21], 0, v[150:151]
	global_load_lds_dwordx4 v[220:221], off
	s_mov_b32 m0, s64
	s_nop 0
	global_load_lds_dwordx4 v[222:223], off
	s_waitcnt vmcnt(8)
	s_waitcnt lgkmcnt(0)
	s_barrier
; #define PG8_STAGE(bufoff, gbase, voff) do { _Pragma("unroll") for (int _i = 0; _i < 2; ++_i) \
;         __builtin_amdgcn_global_load_lds((const unsigned*)((const char*)(gbase) + (voff)[_i]), (PG8_LAS unsigned*)(lds + (bufoff) + ldsw + _i * 8192), 16, 0, 0); } while (0)
; #define PG8_LDA(dst, b, h) do { _Pragma("unroll") for (int m = 0; m < 4; ++m) _Pragma("unroll") for (int k = 0; k < 2; ++k) dst[m][k] = *(const PG8_LAS bf16x8*)(lds + PG8_SA(b, h) + aoff + m * 2048 + k * 1024); } while (0)
; #define PG8_LDB(dst, b, h) do { _Pragma("unroll") for (int n = 0; n < 2; ++n) _Pragma("unroll") for (int k = 0; k < 2; ++k) dst[n][k] = *(const PG8_LAS bf16x8*)(lds + PG8_SB(b, h) + boff + n * 2048 + k * 1024); } while (0)
; #define PG8_MMA(ai, bj, At, Bt) do { __builtin_amdgcn_s_setprio(1); _Pragma("unroll") for (int m = 0; m < 4; ++m) _Pragma("unroll") for (int n = 0; n < 2; ++n) _Pragma("unroll") for (int k = 0; k < 2; ++k) \
;         acc[ai][bj][m][n] = __builtin_amdgcn_mfma_f32_16x16x32_bf16(Bt[n][k], At[m][k], acc[ai][bj][m][n], 0, 0, 0); __builtin_amdgcn_s_setprio(0); } while (0)
; #define PG8_WAIT_V(n) asm volatile("s_waitcnt vmcnt(" #n ")" ::: "memory")
; #define PG8_WAIT_L(n) asm volatile("s_waitcnt lgkmcnt(" #n ")" ::: "memory")
; #define PG8_BAR __builtin_amdgcn_s_barrier()
; #define PG8_SCHED __builtin_amdgcn_sched_barrier(0)
; template <class Epi, class Sched, bool ALIGN_EPI = false, bool SP2 = false>
; __device__ __forceinline__ void gemm_phase(PG8_LAS unsigned char* lds, const Gemm g, const Sched& S, const Epi& E) {
;     ...
;             PG8_WAIT_V(8); PG8_WAIT_L(0); PG8_BAR; PG8_MMA(1, 0, At, B0); PG8_MMA(1, 1, At, B1); PG8_BAR; PG8_SCHED;
;             PG8_LDB(B0, 1, 0); PG8_LDB(B1, 1, 1); PG8_SCHED; PG8_LDA(At, 1, 0); PG8_STAGE(PG8_SA(0, 1), a2 + hstep, voffA);
;             PG8_WAIT_V(8); PG8_WAIT_L(0); PG8_BAR; PG8_MMA(0, 0, At, B0); PG8_MMA(0, 1, At, B1); PG8_BAR; PG8_SCHED;
	s_setprio 1
	v_mfma_f32_16x16x32_bf16 v[102:105], v[82:85], v[178:181], v[102:105]
	v_mfma_f32_16x16x32_bf16 v[98:101], v[138:141], v[178:181], v[98:101]
	v_mfma_f32_16x16x32_bf16 v[94:97], v[82:85], v[186:189], v[94:97]
	v_mfma_f32_16x16x32_bf16 v[90:93], v[138:141], v[186:189], v[90:93]
	v_mfma_f32_16x16x32_bf16 v[78:81], v[82:85], v[194:197], v[78:81]
	v_mfma_f32_16x16x32_bf16 v[74:77], v[138:141], v[194:197], v[74:77]
	v_mfma_f32_16x16x32_bf16 v[70:73], v[82:85], v[202:205], v[70:73]
	v_mfma_f32_16x16x32_bf16 v[66:69], v[138:141], v[202:205], v[66:69]
	v_mfma_f32_16x16x32_bf16 v[102:105], v[86:89], v[182:185], v[102:105]
	v_mfma_f32_16x16x32_bf16 v[98:101], v[142:145], v[182:185], v[98:101]
	v_mfma_f32_16x16x32_bf16 v[94:97], v[86:89], v[190:193], v[94:97]
	v_mfma_f32_16x16x32_bf16 v[90:93], v[142:145], v[190:193], v[90:93]
	v_mfma_f32_16x16x32_bf16 v[78:81], v[86:89], v[198:201], v[78:81]
	v_mfma_f32_16x16x32_bf16 v[74:77], v[142:145], v[198:201], v[74:77]
	v_mfma_f32_16x16x32_bf16 v[70:73], v[86:89], v[206:209], v[70:73]
	v_mfma_f32_16x16x32_bf16 v[66:69], v[142:145], v[206:209], v[66:69]
	v_mfma_f32_16x16x32_bf16 v[30:33], v[158:161], v[178:181], v[30:33]
	v_mfma_f32_16x16x32_bf16 v[26:29], v[170:173], v[178:181], v[26:29]
	v_mfma_f32_16x16x32_bf16 v[22:25], v[158:161], v[186:189], v[22:25]
	v_mfma_f32_16x16x32_bf16 v[18:21], v[170:173], v[186:189], v[18:21]
	v_mfma_f32_16x16x32_bf16 v[14:17], v[158:161], v[194:197], v[14:17]
	v_mfma_f32_16x16x32_bf16 v[10:13], v[170:173], v[194:197], v[10:13]
	v_mfma_f32_16x16x32_bf16 v[6:9], v[158:161], v[202:205], v[6:9]
	v_mfma_f32_16x16x32_bf16 v[2:5], v[170:173], v[202:205], v[2:5]
	v_mfma_f32_16x16x32_bf16 v[30:33], v[162:165], v[182:185], v[30:33]
	v_mfma_f32_16x16x32_bf16 v[26:29], v[174:177], v[182:185], v[26:29]
	v_mfma_f32_16x16x32_bf16 v[22:25], v[162:165], v[190:193], v[22:25]
	v_mfma_f32_16x16x32_bf16 v[18:21], v[174:177], v[190:193], v[18:21]
	v_mfma_f32_16x16x32_bf16 v[14:17], v[162:165], v[198:201], v[14:17]
	v_mfma_f32_16x16x32_bf16 v[10:13], v[174:177], v[198:201], v[10:13]
	v_mfma_f32_16x16x32_bf16 v[6:9], v[162:165], v[206:209], v[6:9]
	v_mfma_f32_16x16x32_bf16 v[2:5], v[174:177], v[206:209], v[2:5]
	s_setprio 0
	s_barrier
	ds_read_b128 v[82:85], v167 offset:32768
	ds_read_b128 v[86:89], v167 offset:33792
	ds_read_b128 v[138:141], v167 offset:34816
	ds_read_b128 v[142:145], v167 offset:35840
	ds_read_b128 v[158:161], v167 offset:49152
	ds_read_b128 v[162:165], v167 offset:50176
	ds_read_b128 v[170:173], v167 offset:51200
	ds_read_b128 v[174:177], v167 offset:52224
	s_mov_b32 m0, s65
	ds_read_b128 v[178:181], v169 offset:32768
	ds_read_b128 v[182:185], v169 offset:33792
	ds_read_b128 v[186:189], v169 offset:34816
	ds_read_b128 v[190:193], v169 offset:35840
	ds_read_b128 v[194:197], v169 offset:36864
	ds_read_b128 v[198:201], v169 offset:37888
	ds_read_b128 v[202:205], v169 offset:38912
	global_load_lds_dwordx4 v154, s[20:21]
	s_mov_b32 m0, s66
	ds_read_b128 v[206:209], v169 offset:39936
	global_load_lds_dwordx4 v156, s[20:21]
	s_waitcnt vmcnt(8)
	s_waitcnt lgkmcnt(0)
	s_barrier
	s_setprio 1
	v_mfma_f32_16x16x32_bf16 v[134:137], v[82:85], v[178:181], v[134:137]
	v_mfma_f32_16x16x32_bf16 v[130:133], v[138:141], v[178:181], v[130:133]
	v_mfma_f32_16x16x32_bf16 v[126:129], v[82:85], v[186:189], v[126:129]
	v_mfma_f32_16x16x32_bf16 v[122:125], v[138:141], v[186:189], v[122:125]
	v_mfma_f32_16x16x32_bf16 v[118:121], v[82:85], v[194:197], v[118:121]
	v_mfma_f32_16x16x32_bf16 v[114:117], v[138:141], v[194:197], v[114:117]
	v_mfma_f32_16x16x32_bf16 v[110:113], v[82:85], v[202:205], v[110:113]
	v_mfma_f32_16x16x32_bf16 v[106:109], v[138:141], v[202:205], v[106:109]
	v_mfma_f32_16x16x32_bf16 v[134:137], v[86:89], v[182:185], v[134:137]
	v_mfma_f32_16x16x32_bf16 v[130:133], v[142:145], v[182:185], v[130:133]
	v_mfma_f32_16x16x32_bf16 v[126:129], v[86:89], v[190:193], v[126:129]
	v_mfma_f32_16x16x32_bf16 v[122:125], v[142:145], v[190:193], v[122:125]
	v_mfma_f32_16x16x32_bf16 v[118:121], v[86:89], v[198:201], v[118:121]
	v_mfma_f32_16x16x32_bf16 v[114:117], v[142:145], v[198:201], v[114:117]
	v_mfma_f32_16x16x32_bf16 v[110:113], v[86:89], v[206:209], v[110:113]
	v_mfma_f32_16x16x32_bf16 v[106:109], v[142:145], v[206:209], v[106:109]
	v_mfma_f32_16x16x32_bf16 v[62:65], v[158:161], v[178:181], v[62:65]
	v_mfma_f32_16x16x32_bf16 v[58:61], v[170:173], v[178:181], v[58:61]
	v_mfma_f32_16x16x32_bf16 v[54:57], v[158:161], v[186:189], v[54:57]
	v_mfma_f32_16x16x32_bf16 v[50:53], v[170:173], v[186:189], v[50:53]
	v_mfma_f32_16x16x32_bf16 v[46:49], v[158:161], v[194:197], v[46:49]
	v_mfma_f32_16x16x32_bf16 v[42:45], v[170:173], v[194:197], v[42:45]
	v_mfma_f32_16x16x32_bf16 v[38:41], v[158:161], v[202:205], v[38:41]
	v_mfma_f32_16x16x32_bf16 v[34:37], v[170:173], v[202:205], v[34:37]
	v_mfma_f32_16x16x32_bf16 v[62:65], v[162:165], v[182:185], v[62:65]
	v_mfma_f32_16x16x32_bf16 v[58:61], v[174:177], v[182:185], v[58:61]
	v_mfma_f32_16x16x32_bf16 v[54:57], v[162:165], v[190:193], v[54:57]
	v_mfma_f32_16x16x32_bf16 v[50:53], v[174:177], v[190:193], v[50:53]
	v_mfma_f32_16x16x32_bf16 v[46:49], v[162:165], v[198:201], v[46:49]
	v_mfma_f32_16x16x32_bf16 v[42:45], v[174:177], v[198:201], v[42:45]
	v_mfma_f32_16x16x32_bf16 v[38:41], v[162:165], v[206:209], v[38:41]
	v_mfma_f32_16x16x32_bf16 v[34:37], v[174:177], v[206:209], v[34:37]
	s_setprio 0
	s_barrier
; #define PG8_STAGE(bufoff, gbase, voff) do { _Pragma("unroll") for (int _i = 0; _i < 2; ++_i) \
;         __builtin_amdgcn_global_load_lds((const unsigned*)((const char*)(gbase) + (voff)[_i]), (PG8_LAS unsigned*)(lds + (bufoff) + ldsw + _i * 8192), 16, 0, 0); } while (0)
; #define PG8_LDA(dst, b, h) do { _Pragma("unroll") for (int m = 0; m < 4; ++m) _Pragma("unroll") for (int k = 0; k < 2; ++k) dst[m][k] = *(const PG8_LAS bf16x8*)(lds + PG8_SA(b, h) + aoff + m * 2048 + k * 1024); } while (0)
; #define PG8_MMA(ai, bj, At, Bt) do { __builtin_amdgcn_s_setprio(1); _Pragma("unroll") for (int m = 0; m < 4; ++m) _Pragma("unroll") for (int n = 0; n < 2; ++n) _Pragma("unroll") for (int k = 0; k < 2; ++k) \
;         acc[ai][bj][m][n] = __builtin_amdgcn_mfma_f32_16x16x32_bf16(Bt[n][k], At[m][k], acc[ai][bj][m][n], 0, 0, 0); __builtin_amdgcn_s_setprio(0); } while (0)
; #define PG8_WAIT_V(n) asm volatile("s_waitcnt vmcnt(" #n ")" ::: "memory")
; #define PG8_WAIT_L(n) asm volatile("s_waitcnt lgkmcnt(" #n ")" ::: "memory")
; #define PG8_BAR __builtin_amdgcn_s_barrier()
; #define PG8_SCHED __builtin_amdgcn_sched_barrier(0)
; template <class Epi, class Sched, bool ALIGN_EPI = false, bool SP2 = false>
; __device__ __forceinline__ void gemm_phase(PG8_LAS unsigned char* lds, const Gemm g, const Sched& S, const Epi& E) {
;     ...
;             PG8_LDA(At, 1, 1); PG8_STAGE(PG8_SB(1, 0), b3, voffB); PG8_STAGE(PG8_SB(1, 1), b3 + hstep, voffB); PG8_STAGE(PG8_SA(1, 0), a3, voffA);
;             PG8_WAIT_V(8); PG8_WAIT_L(0); PG8_BAR; PG8_MMA(1, 0, At, B0); PG8_MMA(1, 1, At, B1); PG8_BAR; PG8_SCHED;
	s_add_i32 m0, s62, 0x17f80
	ds_read_b128 v[178:181], v169 offset:49152
	ds_read_b128 v[182:185], v169 offset:50176
	ds_read_b128 v[186:189], v169 offset:51200
	global_load_lds_dwordx4 v[210:211], off offset:128
	s_add_i32 m0, s62, 0x19f80
	ds_read_b128 v[190:193], v169 offset:52224
	global_load_lds_dwordx4 v[212:213], off offset:128
	s_add_i32 m0, s62, 0x1bf80
	ds_read_b128 v[194:197], v169 offset:53248
	global_load_lds_dwordx4 v[214:215], off offset:128
	s_add_i32 m0, s62, 0x1df80
	ds_read_b128 v[198:201], v169 offset:54272
	global_load_lds_dwordx4 v[218:219], off offset:128
	s_sub_i32 m0, s68, 0x80
	ds_read_b128 v[202:205], v169 offset:55296
	global_load_lds_dwordx4 v[220:221], off offset:128
	s_sub_i32 m0, s69, 0x80
	ds_read_b128 v[206:209], v169 offset:56320
	global_load_lds_dwordx4 v[222:223], off offset:128
	s_waitcnt vmcnt(8)
	s_waitcnt lgkmcnt(0)
	s_barrier
	s_setprio 1
	v_mfma_f32_16x16x32_bf16 v[102:105], v[82:85], v[178:181], v[102:105]
	v_mfma_f32_16x16x32_bf16 v[98:101], v[138:141], v[178:181], v[98:101]
	v_mfma_f32_16x16x32_bf16 v[94:97], v[82:85], v[186:189], v[94:97]
	v_mfma_f32_16x16x32_bf16 v[90:93], v[138:141], v[186:189], v[90:93]
	v_mfma_f32_16x16x32_bf16 v[78:81], v[82:85], v[194:197], v[78:81]
	v_mfma_f32_16x16x32_bf16 v[74:77], v[138:141], v[194:197], v[74:77]
	v_mfma_f32_16x16x32_bf16 v[70:73], v[82:85], v[202:205], v[70:73]
	v_mfma_f32_16x16x32_bf16 v[66:69], v[138:141], v[202:205], v[66:69]
	v_mfma_f32_16x16x32_bf16 v[102:105], v[86:89], v[182:185], v[102:105]
	v_mfma_f32_16x16x32_bf16 v[98:101], v[142:145], v[182:185], v[98:101]
	v_mfma_f32_16x16x32_bf16 v[94:97], v[86:89], v[190:193], v[94:97]
	v_mfma_f32_16x16x32_bf16 v[90:93], v[142:145], v[190:193], v[90:93]
	v_mfma_f32_16x16x32_bf16 v[78:81], v[86:89], v[198:201], v[78:81]
	v_mfma_f32_16x16x32_bf16 v[74:77], v[142:145], v[198:201], v[74:77]
	v_mfma_f32_16x16x32_bf16 v[70:73], v[86:89], v[206:209], v[70:73]
	v_mfma_f32_16x16x32_bf16 v[66:69], v[142:145], v[206:209], v[66:69]
	v_mfma_f32_16x16x32_bf16 v[30:33], v[158:161], v[178:181], v[30:33]
	v_mfma_f32_16x16x32_bf16 v[26:29], v[170:173], v[178:181], v[26:29]
	v_mfma_f32_16x16x32_bf16 v[22:25], v[158:161], v[186:189], v[22:25]
	v_mfma_f32_16x16x32_bf16 v[18:21], v[170:173], v[186:189], v[18:21]
	v_mfma_f32_16x16x32_bf16 v[14:17], v[158:161], v[194:197], v[14:17]
	v_mfma_f32_16x16x32_bf16 v[10:13], v[170:173], v[194:197], v[10:13]
	v_mfma_f32_16x16x32_bf16 v[6:9], v[158:161], v[202:205], v[6:9]
	v_mfma_f32_16x16x32_bf16 v[2:5], v[170:173], v[202:205], v[2:5]
	v_mfma_f32_16x16x32_bf16 v[30:33], v[162:165], v[182:185], v[30:33]
	v_mfma_f32_16x16x32_bf16 v[26:29], v[174:177], v[182:185], v[26:29]
	v_mfma_f32_16x16x32_bf16 v[22:25], v[162:165], v[190:193], v[22:25]
	v_mfma_f32_16x16x32_bf16 v[18:21], v[174:177], v[190:193], v[18:21]
	v_mfma_f32_16x16x32_bf16 v[14:17], v[162:165], v[198:201], v[14:17]
	v_mfma_f32_16x16x32_bf16 v[10:13], v[174:177], v[198:201], v[10:13]
	v_mfma_f32_16x16x32_bf16 v[6:9], v[162:165], v[206:209], v[6:9]
	v_mfma_f32_16x16x32_bf16 v[2:5], v[174:177], v[206:209], v[2:5]
	s_setprio 0
	s_barrier
	s_add_u32 s16, s16, 0x100
	s_addc_u32 s17, s17, 0
	s_add_u32 s33, s33, 0x100
	s_addc_u32 s39, s39, 0
	s_cmp_ge_i32 s44, s67
	s_mov_b32 s20, s44
	s_cbranch_scc0 .LBB0_341
	s_movk_i32 s39, 0x5000

; #define PG8_STAGE(bufoff, gbase, voff) do { _Pragma("unroll") for (int _i = 0; _i < 2; ++_i) \
;         __builtin_amdgcn_global_load_lds((const unsigned*)((const char*)(gbase) + (voff)[_i]), (PG8_LAS unsigned*)(lds + (bufoff) + ldsw + _i * 8192), 16, 0, 0); } while (0)
; #define PG8_LDA(dst, b, h) do { _Pragma("unroll") for (int m = 0; m < 4; ++m) _Pragma("unroll") for (int k = 0; k < 2; ++k) dst[m][k] = *(const PG8_LAS bf16x8*)(lds + PG8_SA(b, h) + aoff + m * 2048 + k * 1024); } while (0)
; #define PG8_LDB(dst, b, h) do { _Pragma("unroll") for (int n = 0; n < 2; ++n) _Pragma("unroll") for (int k = 0; k < 2; ++k) dst[n][k] = *(const PG8_LAS bf16x8*)(lds + PG8_SB(b, h) + boff + n * 2048 + k * 1024); } while (0)
; #define PG8_MMA(ai, bj, At, Bt) do { __builtin_amdgcn_s_setprio(1); _Pragma("unroll") for (int m = 0; m < 4; ++m) _Pragma("unroll") for (int n = 0; n < 2; ++n) _Pragma("unroll") for (int k = 0; k < 2; ++k) \
;         acc[ai][bj][m][n] = __builtin_amdgcn_mfma_f32_16x16x32_bf16(Bt[n][k], At[m][k], acc[ai][bj][m][n], 0, 0, 0); __builtin_amdgcn_s_setprio(0); } while (0)
; #define PG8_WAIT_V(n) asm volatile("s_waitcnt vmcnt(" #n ")" ::: "memory")
; #define PG8_WAIT_L(n) asm volatile("s_waitcnt lgkmcnt(" #n ")" ::: "memory")
; #define PG8_BAR __builtin_amdgcn_s_barrier()
; #define PG8_SCHED __builtin_amdgcn_sched_barrier(0)
; template <class Epi, class Sched, bool ALIGN_EPI = false, bool SP2 = false>
; __device__ __forceinline__ void gemm_phase(PG8_LAS unsigned char* lds, const Gemm g, const Sched& S, const Epi& E) {
;     ...
;         for (int t = 0; t < nt; t += 2) {
;             const bool last = (t == nt - 2);
;             const char* a1 = cA + (size_t)(t + 1) * kstep;
;             const char* a2 = last ? nA : cA + (size_t)(t + 2) * kstep; const char* b2 = last ? nB : cB + (size_t)(t + 2) * kstep;
;             const char* a3 = a2 + kstep; const char* b3 = b2 + kstep;
;             if (last && has_next) S.a_ready(nxt);
;             if constexpr (SP2) {
;             PG8_LDB(B0, 0, 0); PG8_LDB(B1, 0, 1); PG8_SCHED; PG8_LDA(At, 0, 0); PG8_STAGE(PG8_SA(1, 1), a1 + hstep, voffA);
;             PG8_WAIT_V(8); PG8_WAIT_L(0); PG8_BAR; PG8_MMA(0, 0, At, B0); PG8_MMA(0, 1, At, B1); PG8_BAR; PG8_SCHED;
;             PG8_LDA(At, 0, 1); PG8_STAGE(PG8_SB(0, 0), b2, voffB); PG8_STAGE(PG8_SB(0, 1), b2 + hstep, voffB); PG8_STAGE(PG8_SA(0, 0), a2, voffA);
.LBB0_520:
	s_add_i32 s69, s20, 2
	s_add_u32 s70, s8, 0x80
	s_addc_u32 s21, s9, 0
	s_cmp_eq_u32 s63, s20
	s_cselect_b32 s21, s49, s21
	s_cselect_b32 s20, s48, s70
	s_cselect_b32 s71, s51, s53
	s_cselect_b32 s70, s50, s52
	ds_read_b128 v[130:133], v185
	ds_read_b128 v[134:137], v185 offset:1024
	ds_read_b128 v[138:141], v185 offset:2048
	ds_read_b128 v[142:145], v185 offset:3072
	ds_read_b128 v[146:149], v185 offset:16384
	ds_read_b128 v[150:153], v185 offset:17408
	ds_read_b128 v[166:169], v185 offset:18432
	ds_read_b128 v[170:173], v185 offset:19456
	s_add_i32 m0, s56, 0xc000
	ds_read_b128 v[174:177], v189
	ds_read_b128 v[178:181], v189 offset:1024
	ds_read_b128 v[190:193], v189 offset:2048
	ds_read_b128 v[194:197], v189 offset:3072
	ds_read_b128 v[198:201], v189 offset:4096
	ds_read_b128 v[202:205], v189 offset:5120
	ds_read_b128 v[206:209], v189 offset:6144
	global_load_lds_dwordx4 v162, s[8:9]
	s_add_i32 m0, s56, 0xe000
	ds_read_b128 v[210:213], v189 offset:7168
	global_load_lds_dwordx4 v164, s[8:9]
	s_waitcnt vmcnt(8)
	s_waitcnt lgkmcnt(0)
	s_barrier
	s_setprio 1
	v_mfma_f32_16x16x32_bf16 v[126:129], v[130:133], v[174:177], v[126:129]
	v_mfma_f32_16x16x32_bf16 v[122:125], v[138:141], v[174:177], v[122:125]
	v_mfma_f32_16x16x32_bf16 v[110:113], v[130:133], v[190:193], v[110:113]
	v_mfma_f32_16x16x32_bf16 v[106:109], v[138:141], v[190:193], v[106:109]
	v_mfma_f32_16x16x32_bf16 v[94:97], v[130:133], v[198:201], v[94:97]
	v_mfma_f32_16x16x32_bf16 v[90:93], v[138:141], v[198:201], v[90:93]
	v_mfma_f32_16x16x32_bf16 v[78:81], v[130:133], v[206:209], v[78:81]
	v_mfma_f32_16x16x32_bf16 v[74:77], v[138:141], v[206:209], v[74:77]
	v_mfma_f32_16x16x32_bf16 v[126:129], v[134:137], v[178:181], v[126:129]
	v_mfma_f32_16x16x32_bf16 v[122:125], v[142:145], v[178:181], v[122:125]
	v_mfma_f32_16x16x32_bf16 v[110:113], v[134:137], v[194:197], v[110:113]
	v_mfma_f32_16x16x32_bf16 v[106:109], v[142:145], v[194:197], v[106:109]
	v_mfma_f32_16x16x32_bf16 v[94:97], v[134:137], v[202:205], v[94:97]
	v_mfma_f32_16x16x32_bf16 v[90:93], v[142:145], v[202:205], v[90:93]
	v_mfma_f32_16x16x32_bf16 v[78:81], v[134:137], v[210:213], v[78:81]
	v_mfma_f32_16x16x32_bf16 v[74:77], v[142:145], v[210:213], v[74:77]
	v_mfma_f32_16x16x32_bf16 v[118:121], v[146:149], v[174:177], v[118:121]
	v_mfma_f32_16x16x32_bf16 v[114:117], v[166:169], v[174:177], v[114:117]
	v_mfma_f32_16x16x32_bf16 v[102:105], v[146:149], v[190:193], v[102:105]
	v_mfma_f32_16x16x32_bf16 v[98:101], v[166:169], v[190:193], v[98:101]
	v_mfma_f32_16x16x32_bf16 v[86:89], v[146:149], v[198:201], v[86:89]
	v_mfma_f32_16x16x32_bf16 v[82:85], v[166:169], v[198:201], v[82:85]
	v_mfma_f32_16x16x32_bf16 v[70:73], v[146:149], v[206:209], v[70:73]
	v_mfma_f32_16x16x32_bf16 v[66:69], v[166:169], v[206:209], v[66:69]
	v_mfma_f32_16x16x32_bf16 v[118:121], v[150:153], v[178:181], v[118:121]
	v_mfma_f32_16x16x32_bf16 v[114:117], v[170:173], v[178:181], v[114:117]
	v_mfma_f32_16x16x32_bf16 v[102:105], v[150:153], v[194:197], v[102:105]
	v_mfma_f32_16x16x32_bf16 v[98:101], v[170:173], v[194:197], v[98:101]
	v_mfma_f32_16x16x32_bf16 v[86:89], v[150:153], v[202:205], v[86:89]
	v_mfma_f32_16x16x32_bf16 v[82:85], v[170:173], v[202:205], v[82:85]
	v_mfma_f32_16x16x32_bf16 v[70:73], v[150:153], v[210:213], v[70:73]
	v_mfma_f32_16x16x32_bf16 v[66:69], v[170:173], v[210:213], v[66:69]
	s_setprio 0
	s_barrier
	v_lshl_add_u64 v[186:187], s[70:71], 0, v[0:1]
	s_add_i32 m0, s30, 0x10000
	ds_read_b128 v[174:177], v189 offset:16384
	ds_read_b128 v[178:181], v189 offset:17408
	ds_read_b128 v[190:193], v189 offset:18432
	ds_read_b128 v[194:197], v189 offset:19456
	ds_read_b128 v[198:201], v189 offset:20480
	ds_read_b128 v[202:205], v189 offset:21504
	ds_read_b128 v[206:209], v189 offset:22528
	ds_read_b128 v[210:213], v189 offset:23552
	global_load_lds_dwordx4 v[186:187], off
	s_add_i32 m0, s30, 0x12000
	v_lshl_add_u64 v[214:215], s[70:71], 0, v[154:155]
	s_add_u32 s70, s70, s12
	s_addc_u32 s71, s71, s13
	global_load_lds_dwordx4 v[214:215], off
	v_lshl_add_u64 v[218:219], s[70:71], 0, v[0:1]
	s_add_i32 m0, s30, 0x14000
	v_lshl_add_u64 v[220:221], s[70:71], 0, v[154:155]
	global_load_lds_dwordx4 v[218:219], off
	s_add_i32 m0, s30, 0x16000
	v_lshl_add_u64 v[222:223], s[20:21], 0, v[158:159]
	global_load_lds_dwordx4 v[220:221], off
	s_mov_b32 m0, s56
	v_lshl_add_u64 v[224:225], s[20:21], 0, v[156:157]
	global_load_lds_dwordx4 v[222:223], off
	s_mov_b32 m0, s57
	s_nop 0
	global_load_lds_dwordx4 v[224:225], off
	s_waitcnt vmcnt(8)
	s_waitcnt lgkmcnt(0)
	s_barrier
; #define PG8_STAGE(bufoff, gbase, voff) do { _Pragma("unroll") for (int _i = 0; _i < 2; ++_i) \
;         __builtin_amdgcn_global_load_lds((const unsigned*)((const char*)(gbase) + (voff)[_i]), (PG8_LAS unsigned*)(lds + (bufoff) + ldsw + _i * 8192), 16, 0, 0); } while (0)
; #define PG8_LDA(dst, b, h) do { _Pragma("unroll") for (int m = 0; m < 4; ++m) _Pragma("unroll") for (int k = 0; k < 2; ++k) dst[m][k] = *(const PG8_LAS bf16x8*)(lds + PG8_SA(b, h) + aoff + m * 2048 + k * 1024); } while (0)
; #define PG8_LDB(dst, b, h) do { _Pragma("unroll") for (int n = 0; n < 2; ++n) _Pragma("unroll") for (int k = 0; k < 2; ++k) dst[n][k] = *(const PG8_LAS bf16x8*)(lds + PG8_SB(b, h) + boff + n * 2048 + k * 1024); } while (0)
; #define PG8_MMA(ai, bj, At, Bt) do { __builtin_amdgcn_s_setprio(1); _Pragma("unroll") for (int m = 0; m < 4; ++m) _Pragma("unroll") for (int n = 0; n < 2; ++n) _Pragma("unroll") for (int k = 0; k < 2; ++k) \
;         acc[ai][bj][m][n] = __builtin_amdgcn_mfma_f32_16x16x32_bf16(Bt[n][k], At[m][k], acc[ai][bj][m][n], 0, 0, 0); __builtin_amdgcn_s_setprio(0); } while (0)
; #define PG8_WAIT_V(n) asm volatile("s_waitcnt vmcnt(" #n ")" ::: "memory")
; #define PG8_WAIT_L(n) asm volatile("s_waitcnt lgkmcnt(" #n ")" ::: "memory")
; #define PG8_BAR __builtin_amdgcn_s_barrier()
; #define PG8_SCHED __builtin_amdgcn_sched_barrier(0)
; template <class Epi, class Sched, bool ALIGN_EPI = false, bool SP2 = false>
; __device__ __forceinline__ void gemm_phase(PG8_LAS unsigned char* lds, const Gemm g, const Sched& S, const Epi& E) {
;     ...
;             PG8_WAIT_V(8); PG8_WAIT_L(0); PG8_BAR; PG8_MMA(1, 0, At, B0); PG8_MMA(1, 1, At, B1); PG8_BAR; PG8_SCHED;
;             PG8_LDB(B0, 1, 0); PG8_LDB(B1, 1, 1); PG8_SCHED; PG8_LDA(At, 1, 0); PG8_STAGE(PG8_SA(0, 1), a2 + hstep, voffA);
;             PG8_WAIT_V(8); PG8_WAIT_L(0); PG8_BAR; PG8_MMA(0, 0, At, B0); PG8_MMA(0, 1, At, B1); PG8_BAR; PG8_SCHED;
	s_setprio 1
	v_mfma_f32_16x16x32_bf16 v[62:65], v[130:133], v[174:177], v[62:65]
	v_mfma_f32_16x16x32_bf16 v[58:61], v[138:141], v[174:177], v[58:61]
	v_mfma_f32_16x16x32_bf16 v[46:49], v[130:133], v[190:193], v[46:49]
	v_mfma_f32_16x16x32_bf16 v[42:45], v[138:141], v[190:193], v[42:45]
	v_mfma_f32_16x16x32_bf16 v[30:33], v[130:133], v[198:201], v[30:33]
	v_mfma_f32_16x16x32_bf16 v[26:29], v[138:141], v[198:201], v[26:29]
	v_mfma_f32_16x16x32_bf16 v[14:17], v[130:133], v[206:209], v[14:17]
	v_mfma_f32_16x16x32_bf16 v[10:13], v[138:141], v[206:209], v[10:13]
	v_mfma_f32_16x16x32_bf16 v[62:65], v[134:137], v[178:181], v[62:65]
	v_mfma_f32_16x16x32_bf16 v[58:61], v[142:145], v[178:181], v[58:61]
	v_mfma_f32_16x16x32_bf16 v[46:49], v[134:137], v[194:197], v[46:49]
	v_mfma_f32_16x16x32_bf16 v[42:45], v[142:145], v[194:197], v[42:45]
	v_mfma_f32_16x16x32_bf16 v[30:33], v[134:137], v[202:205], v[30:33]
	v_mfma_f32_16x16x32_bf16 v[26:29], v[142:145], v[202:205], v[26:29]
	v_mfma_f32_16x16x32_bf16 v[14:17], v[134:137], v[210:213], v[14:17]
	v_mfma_f32_16x16x32_bf16 v[10:13], v[142:145], v[210:213], v[10:13]
	v_mfma_f32_16x16x32_bf16 v[54:57], v[146:149], v[174:177], v[54:57]
	v_mfma_f32_16x16x32_bf16 v[50:53], v[166:169], v[174:177], v[50:53]
	v_mfma_f32_16x16x32_bf16 v[38:41], v[146:149], v[190:193], v[38:41]
	v_mfma_f32_16x16x32_bf16 v[34:37], v[166:169], v[190:193], v[34:37]
	v_mfma_f32_16x16x32_bf16 v[22:25], v[146:149], v[198:201], v[22:25]
	v_mfma_f32_16x16x32_bf16 v[18:21], v[166:169], v[198:201], v[18:21]
	v_mfma_f32_16x16x32_bf16 v[6:9], v[146:149], v[206:209], v[6:9]
	v_mfma_f32_16x16x32_bf16 v[2:5], v[166:169], v[206:209], v[2:5]
	v_mfma_f32_16x16x32_bf16 v[54:57], v[150:153], v[178:181], v[54:57]
	v_mfma_f32_16x16x32_bf16 v[50:53], v[170:173], v[178:181], v[50:53]
	v_mfma_f32_16x16x32_bf16 v[38:41], v[150:153], v[194:197], v[38:41]
	v_mfma_f32_16x16x32_bf16 v[34:37], v[170:173], v[194:197], v[34:37]
	v_mfma_f32_16x16x32_bf16 v[22:25], v[150:153], v[202:205], v[22:25]
	v_mfma_f32_16x16x32_bf16 v[18:21], v[170:173], v[202:205], v[18:21]
	v_mfma_f32_16x16x32_bf16 v[6:9], v[150:153], v[210:213], v[6:9]
	v_mfma_f32_16x16x32_bf16 v[2:5], v[170:173], v[210:213], v[2:5]
	s_setprio 0
	s_barrier
	ds_read_b128 v[130:133], v185 offset:32768
	ds_read_b128 v[134:137], v185 offset:33792
	ds_read_b128 v[138:141], v185 offset:34816
	ds_read_b128 v[142:145], v185 offset:35840
	ds_read_b128 v[146:149], v185 offset:49152
	ds_read_b128 v[150:153], v185 offset:50176
	ds_read_b128 v[166:169], v185 offset:51200
	ds_read_b128 v[170:173], v185 offset:52224
	s_mov_b32 m0, s58
	ds_read_b128 v[174:177], v189 offset:32768
	ds_read_b128 v[178:181], v189 offset:33792
	ds_read_b128 v[190:193], v189 offset:34816
	ds_read_b128 v[194:197], v189 offset:35840
	ds_read_b128 v[198:201], v189 offset:36864
	ds_read_b128 v[202:205], v189 offset:37888
	ds_read_b128 v[206:209], v189 offset:38912
	global_load_lds_dwordx4 v162, s[20:21]
	s_mov_b32 m0, s59
	ds_read_b128 v[210:213], v189 offset:39936
	global_load_lds_dwordx4 v164, s[20:21]
	s_waitcnt vmcnt(8)
	s_waitcnt lgkmcnt(0)
	s_barrier
	s_setprio 1
	v_mfma_f32_16x16x32_bf16 v[126:129], v[130:133], v[174:177], v[126:129]
	v_mfma_f32_16x16x32_bf16 v[122:125], v[138:141], v[174:177], v[122:125]
	v_mfma_f32_16x16x32_bf16 v[110:113], v[130:133], v[190:193], v[110:113]
	v_mfma_f32_16x16x32_bf16 v[106:109], v[138:141], v[190:193], v[106:109]
	v_mfma_f32_16x16x32_bf16 v[94:97], v[130:133], v[198:201], v[94:97]
	v_mfma_f32_16x16x32_bf16 v[90:93], v[138:141], v[198:201], v[90:93]
	v_mfma_f32_16x16x32_bf16 v[78:81], v[130:133], v[206:209], v[78:81]
	v_mfma_f32_16x16x32_bf16 v[74:77], v[138:141], v[206:209], v[74:77]
	v_mfma_f32_16x16x32_bf16 v[126:129], v[134:137], v[178:181], v[126:129]
	v_mfma_f32_16x16x32_bf16 v[122:125], v[142:145], v[178:181], v[122:125]
	v_mfma_f32_16x16x32_bf16 v[110:113], v[134:137], v[194:197], v[110:113]
	v_mfma_f32_16x16x32_bf16 v[106:109], v[142:145], v[194:197], v[106:109]
	v_mfma_f32_16x16x32_bf16 v[94:97], v[134:137], v[202:205], v[94:97]
	v_mfma_f32_16x16x32_bf16 v[90:93], v[142:145], v[202:205], v[90:93]
	v_mfma_f32_16x16x32_bf16 v[78:81], v[134:137], v[210:213], v[78:81]
	v_mfma_f32_16x16x32_bf16 v[74:77], v[142:145], v[210:213], v[74:77]
	v_mfma_f32_16x16x32_bf16 v[118:121], v[146:149], v[174:177], v[118:121]
	v_mfma_f32_16x16x32_bf16 v[114:117], v[166:169], v[174:177], v[114:117]
	v_mfma_f32_16x16x32_bf16 v[102:105], v[146:149], v[190:193], v[102:105]
	v_mfma_f32_16x16x32_bf16 v[98:101], v[166:169], v[190:193], v[98:101]
	v_mfma_f32_16x16x32_bf16 v[86:89], v[146:149], v[198:201], v[86:89]
	v_mfma_f32_16x16x32_bf16 v[82:85], v[166:169], v[198:201], v[82:85]
	v_mfma_f32_16x16x32_bf16 v[70:73], v[146:149], v[206:209], v[70:73]
	v_mfma_f32_16x16x32_bf16 v[66:69], v[166:169], v[206:209], v[66:69]
	v_mfma_f32_16x16x32_bf16 v[118:121], v[150:153], v[178:181], v[118:121]
	v_mfma_f32_16x16x32_bf16 v[114:117], v[170:173], v[178:181], v[114:117]
	v_mfma_f32_16x16x32_bf16 v[102:105], v[150:153], v[194:197], v[102:105]
	v_mfma_f32_16x16x32_bf16 v[98:101], v[170:173], v[194:197], v[98:101]
	v_mfma_f32_16x16x32_bf16 v[86:89], v[150:153], v[202:205], v[86:89]
	v_mfma_f32_16x16x32_bf16 v[82:85], v[170:173], v[202:205], v[82:85]
	v_mfma_f32_16x16x32_bf16 v[70:73], v[150:153], v[210:213], v[70:73]
	v_mfma_f32_16x16x32_bf16 v[66:69], v[170:173], v[210:213], v[66:69]
	s_setprio 0
	s_barrier
; #define PG8_STAGE(bufoff, gbase, voff) do { _Pragma("unroll") for (int _i = 0; _i < 2; ++_i) \
;         __builtin_amdgcn_global_load_lds((const unsigned*)((const char*)(gbase) + (voff)[_i]), (PG8_LAS unsigned*)(lds + (bufoff) + ldsw + _i * 8192), 16, 0, 0); } while (0)
; #define PG8_LDA(dst, b, h) do { _Pragma("unroll") for (int m = 0; m < 4; ++m) _Pragma("unroll") for (int k = 0; k < 2; ++k) dst[m][k] = *(const PG8_LAS bf16x8*)(lds + PG8_SA(b, h) + aoff + m * 2048 + k * 1024); } while (0)
; #define PG8_MMA(ai, bj, At, Bt) do { __builtin_amdgcn_s_setprio(1); _Pragma("unroll") for (int m = 0; m < 4; ++m) _Pragma("unroll") for (int n = 0; n < 2; ++n) _Pragma("unroll") for (int k = 0; k < 2; ++k) \
;         acc[ai][bj][m][n] = __builtin_amdgcn_mfma_f32_16x16x32_bf16(Bt[n][k], At[m][k], acc[ai][bj][m][n], 0, 0, 0); __builtin_amdgcn_s_setprio(0); } while (0)
; #define PG8_WAIT_V(n) asm volatile("s_waitcnt vmcnt(" #n ")" ::: "memory")
; #define PG8_WAIT_L(n) asm volatile("s_waitcnt lgkmcnt(" #n ")" ::: "memory")
; #define PG8_BAR __builtin_amdgcn_s_barrier()
; #define PG8_SCHED __builtin_amdgcn_sched_barrier(0)
; template <class Epi, class Sched, bool ALIGN_EPI = false, bool SP2 = false>
; __device__ __forceinline__ void gemm_phase(PG8_LAS unsigned char* lds, const Gemm g, const Sched& S, const Epi& E) {
;     ...
;             PG8_LDA(At, 1, 1); PG8_STAGE(PG8_SB(1, 0), b3, voffB); PG8_STAGE(PG8_SB(1, 1), b3 + hstep, voffB); PG8_STAGE(PG8_SA(1, 0), a3, voffA);
;             PG8_WAIT_V(8); PG8_WAIT_L(0); PG8_BAR; PG8_MMA(1, 0, At, B0); PG8_MMA(1, 1, At, B1); PG8_BAR; PG8_SCHED;
	s_add_i32 m0, s30, 0x17f80
	ds_read_b128 v[174:177], v189 offset:49152
	ds_read_b128 v[178:181], v189 offset:50176
	ds_read_b128 v[190:193], v189 offset:51200
	global_load_lds_dwordx4 v[186:187], off offset:128
	s_add_i32 m0, s30, 0x19f80
	ds_read_b128 v[194:197], v189 offset:52224
	global_load_lds_dwordx4 v[214:215], off offset:128
	s_add_i32 m0, s30, 0x1bf80
	ds_read_b128 v[198:201], v189 offset:53248
	global_load_lds_dwordx4 v[218:219], off offset:128
	s_add_i32 m0, s30, 0x1df80
	ds_read_b128 v[202:205], v189 offset:54272
	global_load_lds_dwordx4 v[220:221], off offset:128
	s_sub_i32 m0, s60, 0x80
	ds_read_b128 v[206:209], v189 offset:55296
	global_load_lds_dwordx4 v[222:223], off offset:128
	s_sub_i32 m0, s61, 0x80
	ds_read_b128 v[210:213], v189 offset:56320
	global_load_lds_dwordx4 v[224:225], off offset:128
	s_waitcnt vmcnt(8)
	s_waitcnt lgkmcnt(0)
	s_barrier
	s_setprio 1
	v_mfma_f32_16x16x32_bf16 v[62:65], v[130:133], v[174:177], v[62:65]
	v_mfma_f32_16x16x32_bf16 v[58:61], v[138:141], v[174:177], v[58:61]
	v_mfma_f32_16x16x32_bf16 v[46:49], v[130:133], v[190:193], v[46:49]
	v_mfma_f32_16x16x32_bf16 v[42:45], v[138:141], v[190:193], v[42:45]
	v_mfma_f32_16x16x32_bf16 v[30:33], v[130:133], v[198:201], v[30:33]
	v_mfma_f32_16x16x32_bf16 v[26:29], v[138:141], v[198:201], v[26:29]
	v_mfma_f32_16x16x32_bf16 v[14:17], v[130:133], v[206:209], v[14:17]
	v_mfma_f32_16x16x32_bf16 v[10:13], v[138:141], v[206:209], v[10:13]
	v_mfma_f32_16x16x32_bf16 v[62:65], v[134:137], v[178:181], v[62:65]
	v_mfma_f32_16x16x32_bf16 v[58:61], v[142:145], v[178:181], v[58:61]
	v_mfma_f32_16x16x32_bf16 v[46:49], v[134:137], v[194:197], v[46:49]
	v_mfma_f32_16x16x32_bf16 v[42:45], v[142:145], v[194:197], v[42:45]
	v_mfma_f32_16x16x32_bf16 v[30:33], v[134:137], v[202:205], v[30:33]
	v_mfma_f32_16x16x32_bf16 v[26:29], v[142:145], v[202:205], v[26:29]
	v_mfma_f32_16x16x32_bf16 v[14:17], v[134:137], v[210:213], v[14:17]
	v_mfma_f32_16x16x32_bf16 v[10:13], v[142:145], v[210:213], v[10:13]
	v_mfma_f32_16x16x32_bf16 v[54:57], v[146:149], v[174:177], v[54:57]
	v_mfma_f32_16x16x32_bf16 v[50:53], v[166:169], v[174:177], v[50:53]
	v_mfma_f32_16x16x32_bf16 v[38:41], v[146:149], v[190:193], v[38:41]
	v_mfma_f32_16x16x32_bf16 v[34:37], v[166:169], v[190:193], v[34:37]
	v_mfma_f32_16x16x32_bf16 v[22:25], v[146:149], v[198:201], v[22:25]
	v_mfma_f32_16x16x32_bf16 v[18:21], v[166:169], v[198:201], v[18:21]
	v_mfma_f32_16x16x32_bf16 v[6:9], v[146:149], v[206:209], v[6:9]
	v_mfma_f32_16x16x32_bf16 v[2:5], v[166:169], v[206:209], v[2:5]
	v_mfma_f32_16x16x32_bf16 v[54:57], v[150:153], v[178:181], v[54:57]
	v_mfma_f32_16x16x32_bf16 v[50:53], v[170:173], v[178:181], v[50:53]
	v_mfma_f32_16x16x32_bf16 v[38:41], v[150:153], v[194:197], v[38:41]
	v_mfma_f32_16x16x32_bf16 v[34:37], v[170:173], v[194:197], v[34:37]
	v_mfma_f32_16x16x32_bf16 v[22:25], v[150:153], v[202:205], v[22:25]
	v_mfma_f32_16x16x32_bf16 v[18:21], v[170:173], v[202:205], v[18:21]
	v_mfma_f32_16x16x32_bf16 v[6:9], v[150:153], v[210:213], v[6:9]
	v_mfma_f32_16x16x32_bf16 v[2:5], v[170:173], v[210:213], v[2:5]
	s_setprio 0
	s_barrier
	s_add_u32 s8, s8, 0x100
	s_addc_u32 s9, s9, 0
	s_add_u32 s52, s52, 0x100
	s_addc_u32 s53, s53, 0
	s_cmp_ge_i32 s69, s62
	s_mov_b32 s20, s69
	s_cbranch_scc0 .LBB0_520

; #define PG8_STAGE(bufoff, gbase, voff) do { _Pragma("unroll") for (int _i = 0; _i < 2; ++_i) \
;         __builtin_amdgcn_global_load_lds((const unsigned*)((const char*)(gbase) + (voff)[_i]), (PG8_LAS unsigned*)(lds + (bufoff) + ldsw + _i * 8192), 16, 0, 0); } while (0)
; #define PG8_LDA(dst, b, h) do { _Pragma("unroll") for (int m = 0; m < 4; ++m) _Pragma("unroll") for (int k = 0; k < 2; ++k) dst[m][k] = *(const PG8_LAS bf16x8*)(lds + PG8_SA(b, h) + aoff + m * 2048 + k * 1024); } while (0)
; #define PG8_LDB(dst, b, h) do { _Pragma("unroll") for (int n = 0; n < 2; ++n) _Pragma("unroll") for (int k = 0; k < 2; ++k) dst[n][k] = *(const PG8_LAS bf16x8*)(lds + PG8_SB(b, h) + boff + n * 2048 + k * 1024); } while (0)
; #define PG8_MMA(ai, bj, At, Bt) do { __builtin_amdgcn_s_setprio(1); _Pragma("unroll") for (int m = 0; m < 4; ++m) _Pragma("unroll") for (int n = 0; n < 2; ++n) _Pragma("unroll") for (int k = 0; k < 2; ++k) \
;         acc[ai][bj][m][n] = __builtin_amdgcn_mfma_f32_16x16x32_bf16(Bt[n][k], At[m][k], acc[ai][bj][m][n], 0, 0, 0); __builtin_amdgcn_s_setprio(0); } while (0)
; #define PG8_WAIT_V(n) asm volatile("s_waitcnt vmcnt(" #n ")" ::: "memory")
; #define PG8_WAIT_L(n) asm volatile("s_waitcnt lgkmcnt(" #n ")" ::: "memory")
; #define PG8_BAR __builtin_amdgcn_s_barrier()
; #define PG8_SCHED __builtin_amdgcn_sched_barrier(0)
; template <class Epi, class Sched, bool ALIGN_EPI = false, bool SP2 = false>
; __device__ __forceinline__ void gemm_phase(PG8_LAS unsigned char* lds, const Gemm g, const Sched& S, const Epi& E) {
;     ...
;         for (int t = 0; t < nt; t += 2) {
;             const bool last = (t == nt - 2);
;             const char* a1 = cA + (size_t)(t + 1) * kstep;
;             const char* a2 = last ? nA : cA + (size_t)(t + 2) * kstep; const char* b2 = last ? nB : cB + (size_t)(t + 2) * kstep;
;             const char* a3 = a2 + kstep; const char* b3 = b2 + kstep;
;             if (last && has_next) S.a_ready(nxt);
;             if constexpr (SP2) {
;             PG8_LDB(B0, 0, 0); PG8_LDB(B1, 0, 1); PG8_SCHED; PG8_LDA(At, 0, 0); PG8_STAGE(PG8_SA(1, 1), a1 + hstep, voffA);
;             PG8_WAIT_V(8); PG8_WAIT_L(0); PG8_BAR; PG8_MMA(0, 0, At, B0); PG8_MMA(0, 1, At, B1); PG8_BAR; PG8_SCHED;
;             PG8_LDA(At, 0, 1); PG8_STAGE(PG8_SB(0, 0), b2, voffB); PG8_STAGE(PG8_SB(0, 1), b2 + hstep, voffB); PG8_STAGE(PG8_SA(0, 0), a2, voffA);
.LBB0_570:
	s_add_i32 s78, s20, 2
	s_add_u32 s79, s10, 0x80
	s_addc_u32 s21, s11, 0
	s_cmp_eq_u32 s68, s20
	s_cselect_b32 s21, s59, s21
	s_cselect_b32 s20, s58, s79
	s_cselect_b32 s81, s61, s63
	s_cselect_b32 s80, s60, s62
	ds_read_b128 v[82:85], v246
	ds_read_b128 v[98:101], v246 offset:1024
	ds_read_b128 v[102:105], v246 offset:2048
	ds_read_b128 v[106:109], v246 offset:3072
	ds_read_b128 v[146:149], v246 offset:16384
	ds_read_b128 v[150:153], v246 offset:17408
	ds_read_b128 v[154:157], v246 offset:18432
	ds_read_b128 v[158:161], v246 offset:19456
	s_add_i32 m0, s64, 0xc000
	ds_read_b128 v[162:165], v249
	ds_read_b128 v[166:169], v249 offset:1024
	ds_read_b128 v[170:173], v249 offset:2048
	ds_read_b128 v[174:177], v249 offset:3072
	ds_read_b128 v[178:181], v249 offset:4096
	ds_read_b128 v[182:185], v249 offset:5120
	ds_read_b128 v[186:189], v249 offset:6144
	global_load_lds_dwordx4 v224, s[10:11]
	s_add_i32 m0, s64, 0xe000
	ds_read_b128 v[190:193], v249 offset:7168
	global_load_lds_dwordx4 v226, s[10:11]
	s_waitcnt vmcnt(8)
	s_waitcnt lgkmcnt(0)
	s_barrier
	s_setprio 1
	v_mfma_f32_16x16x32_bf16 v[142:145], v[82:85], v[162:165], v[142:145]
	v_mfma_f32_16x16x32_bf16 v[138:141], v[102:105], v[162:165], v[138:141]
	v_mfma_f32_16x16x32_bf16 v[126:129], v[82:85], v[170:173], v[126:129]
	v_mfma_f32_16x16x32_bf16 v[122:125], v[102:105], v[170:173], v[122:125]
	v_mfma_f32_16x16x32_bf16 v[110:113], v[82:85], v[178:181], v[110:113]
	v_mfma_f32_16x16x32_bf16 v[94:97], v[102:105], v[178:181], v[94:97]
	v_mfma_f32_16x16x32_bf16 v[78:81], v[82:85], v[186:189], v[78:81]
	v_mfma_f32_16x16x32_bf16 v[74:77], v[102:105], v[186:189], v[74:77]
	v_mfma_f32_16x16x32_bf16 v[142:145], v[98:101], v[166:169], v[142:145]
	v_mfma_f32_16x16x32_bf16 v[138:141], v[106:109], v[166:169], v[138:141]
	v_mfma_f32_16x16x32_bf16 v[126:129], v[98:101], v[174:177], v[126:129]
	v_mfma_f32_16x16x32_bf16 v[122:125], v[106:109], v[174:177], v[122:125]
	v_mfma_f32_16x16x32_bf16 v[110:113], v[98:101], v[182:185], v[110:113]
	v_mfma_f32_16x16x32_bf16 v[94:97], v[106:109], v[182:185], v[94:97]
	v_mfma_f32_16x16x32_bf16 v[78:81], v[98:101], v[190:193], v[78:81]
	v_mfma_f32_16x16x32_bf16 v[74:77], v[106:109], v[190:193], v[74:77]
	v_mfma_f32_16x16x32_bf16 v[134:137], v[146:149], v[162:165], v[134:137]
	v_mfma_f32_16x16x32_bf16 v[130:133], v[154:157], v[162:165], v[130:133]
	v_mfma_f32_16x16x32_bf16 v[118:121], v[146:149], v[170:173], v[118:121]
	v_mfma_f32_16x16x32_bf16 v[114:117], v[154:157], v[170:173], v[114:117]
	v_mfma_f32_16x16x32_bf16 v[90:93], v[146:149], v[178:181], v[90:93]
	v_mfma_f32_16x16x32_bf16 v[86:89], v[154:157], v[178:181], v[86:89]
	v_mfma_f32_16x16x32_bf16 v[70:73], v[146:149], v[186:189], v[70:73]
	v_mfma_f32_16x16x32_bf16 v[66:69], v[154:157], v[186:189], v[66:69]
	v_mfma_f32_16x16x32_bf16 v[134:137], v[150:153], v[166:169], v[134:137]
	v_mfma_f32_16x16x32_bf16 v[130:133], v[158:161], v[166:169], v[130:133]
	v_mfma_f32_16x16x32_bf16 v[118:121], v[150:153], v[174:177], v[118:121]
	v_mfma_f32_16x16x32_bf16 v[114:117], v[158:161], v[174:177], v[114:117]
	v_mfma_f32_16x16x32_bf16 v[90:93], v[150:153], v[182:185], v[90:93]
	v_mfma_f32_16x16x32_bf16 v[86:89], v[158:161], v[182:185], v[86:89]
	v_mfma_f32_16x16x32_bf16 v[70:73], v[150:153], v[190:193], v[70:73]
	v_mfma_f32_16x16x32_bf16 v[66:69], v[158:161], v[190:193], v[66:69]
	s_setprio 0
	s_barrier
	v_lshl_add_u64 v[194:195], s[80:81], 0, v[0:1]
	s_add_i32 m0, s22, 0x10000
	ds_read_b128 v[162:165], v249 offset:16384
	ds_read_b128 v[166:169], v249 offset:17408
	ds_read_b128 v[170:173], v249 offset:18432
	ds_read_b128 v[174:177], v249 offset:19456
	ds_read_b128 v[178:181], v249 offset:20480
	ds_read_b128 v[182:185], v249 offset:21504
	ds_read_b128 v[186:189], v249 offset:22528
	ds_read_b128 v[190:193], v249 offset:23552
	global_load_lds_dwordx4 v[194:195], off
	s_add_i32 m0, s22, 0x12000
	v_lshl_add_u64 v[196:197], s[80:81], 0, v[218:219]
	s_add_u32 s80, s80, s46
	s_addc_u32 s81, s81, s47
	global_load_lds_dwordx4 v[196:197], off
	v_lshl_add_u64 v[198:199], s[80:81], 0, v[0:1]
	s_add_i32 m0, s22, 0x14000
	v_lshl_add_u64 v[200:201], s[80:81], 0, v[218:219]
	global_load_lds_dwordx4 v[198:199], off
	s_add_i32 m0, s22, 0x16000
	v_lshl_add_u64 v[202:203], s[20:21], 0, v[0:1]
	global_load_lds_dwordx4 v[200:201], off
	s_mov_b32 m0, s64
	v_lshl_add_u64 v[204:205], s[20:21], 0, v[218:219]
	global_load_lds_dwordx4 v[202:203], off
	s_mov_b32 m0, s30
	s_nop 0
	global_load_lds_dwordx4 v[204:205], off
	s_waitcnt vmcnt(8)
	s_waitcnt lgkmcnt(0)
	s_barrier
; #define PG8_STAGE(bufoff, gbase, voff) do { _Pragma("unroll") for (int _i = 0; _i < 2; ++_i) \
;         __builtin_amdgcn_global_load_lds((const unsigned*)((const char*)(gbase) + (voff)[_i]), (PG8_LAS unsigned*)(lds + (bufoff) + ldsw + _i * 8192), 16, 0, 0); } while (0)
; #define PG8_LDA(dst, b, h) do { _Pragma("unroll") for (int m = 0; m < 4; ++m) _Pragma("unroll") for (int k = 0; k < 2; ++k) dst[m][k] = *(const PG8_LAS bf16x8*)(lds + PG8_SA(b, h) + aoff + m * 2048 + k * 1024); } while (0)
; #define PG8_LDB(dst, b, h) do { _Pragma("unroll") for (int n = 0; n < 2; ++n) _Pragma("unroll") for (int k = 0; k < 2; ++k) dst[n][k] = *(const PG8_LAS bf16x8*)(lds + PG8_SB(b, h) + boff + n * 2048 + k * 1024); } while (0)
; #define PG8_MMA(ai, bj, At, Bt) do { __builtin_amdgcn_s_setprio(1); _Pragma("unroll") for (int m = 0; m < 4; ++m) _Pragma("unroll") for (int n = 0; n < 2; ++n) _Pragma("unroll") for (int k = 0; k < 2; ++k) \
;         acc[ai][bj][m][n] = __builtin_amdgcn_mfma_f32_16x16x32_bf16(Bt[n][k], At[m][k], acc[ai][bj][m][n], 0, 0, 0); __builtin_amdgcn_s_setprio(0); } while (0)
; #define PG8_WAIT_V(n) asm volatile("s_waitcnt vmcnt(" #n ")" ::: "memory")
; #define PG8_WAIT_L(n) asm volatile("s_waitcnt lgkmcnt(" #n ")" ::: "memory")
; #define PG8_BAR __builtin_amdgcn_s_barrier()
; #define PG8_SCHED __builtin_amdgcn_sched_barrier(0)
; template <class Epi, class Sched, bool ALIGN_EPI = false, bool SP2 = false>
; __device__ __forceinline__ void gemm_phase(PG8_LAS unsigned char* lds, const Gemm g, const Sched& S, const Epi& E) {
;     ...
;             PG8_WAIT_V(8); PG8_WAIT_L(0); PG8_BAR; PG8_MMA(1, 0, At, B0); PG8_MMA(1, 1, At, B1); PG8_BAR; PG8_SCHED;
;             PG8_LDB(B0, 1, 0); PG8_LDB(B1, 1, 1); PG8_SCHED; PG8_LDA(At, 1, 0); PG8_STAGE(PG8_SA(0, 1), a2 + hstep, voffA);
;             PG8_WAIT_V(8); PG8_WAIT_L(0); PG8_BAR; PG8_MMA(0, 0, At, B0); PG8_MMA(0, 1, At, B1); PG8_BAR; PG8_SCHED;
	s_setprio 1
	v_mfma_f32_16x16x32_bf16 v[62:65], v[82:85], v[162:165], v[62:65]
	v_mfma_f32_16x16x32_bf16 v[58:61], v[102:105], v[162:165], v[58:61]
	v_mfma_f32_16x16x32_bf16 v[46:49], v[82:85], v[170:173], v[46:49]
	v_mfma_f32_16x16x32_bf16 v[42:45], v[102:105], v[170:173], v[42:45]
	v_mfma_f32_16x16x32_bf16 v[30:33], v[82:85], v[178:181], v[30:33]
	v_mfma_f32_16x16x32_bf16 v[26:29], v[102:105], v[178:181], v[26:29]
	v_mfma_f32_16x16x32_bf16 v[14:17], v[82:85], v[186:189], v[14:17]
	v_mfma_f32_16x16x32_bf16 v[10:13], v[102:105], v[186:189], v[10:13]
	v_mfma_f32_16x16x32_bf16 v[62:65], v[98:101], v[166:169], v[62:65]
	v_mfma_f32_16x16x32_bf16 v[58:61], v[106:109], v[166:169], v[58:61]
	v_mfma_f32_16x16x32_bf16 v[46:49], v[98:101], v[174:177], v[46:49]
	v_mfma_f32_16x16x32_bf16 v[42:45], v[106:109], v[174:177], v[42:45]
	v_mfma_f32_16x16x32_bf16 v[30:33], v[98:101], v[182:185], v[30:33]
	v_mfma_f32_16x16x32_bf16 v[26:29], v[106:109], v[182:185], v[26:29]
	v_mfma_f32_16x16x32_bf16 v[14:17], v[98:101], v[190:193], v[14:17]
	v_mfma_f32_16x16x32_bf16 v[10:13], v[106:109], v[190:193], v[10:13]
	v_mfma_f32_16x16x32_bf16 v[54:57], v[146:149], v[162:165], v[54:57]
	v_mfma_f32_16x16x32_bf16 v[50:53], v[154:157], v[162:165], v[50:53]
	v_mfma_f32_16x16x32_bf16 v[38:41], v[146:149], v[170:173], v[38:41]
	v_mfma_f32_16x16x32_bf16 v[34:37], v[154:157], v[170:173], v[34:37]
	v_mfma_f32_16x16x32_bf16 v[22:25], v[146:149], v[178:181], v[22:25]
	v_mfma_f32_16x16x32_bf16 v[18:21], v[154:157], v[178:181], v[18:21]
	v_mfma_f32_16x16x32_bf16 v[6:9], v[146:149], v[186:189], v[6:9]
	v_mfma_f32_16x16x32_bf16 v[2:5], v[154:157], v[186:189], v[2:5]
	v_mfma_f32_16x16x32_bf16 v[54:57], v[150:153], v[166:169], v[54:57]
	v_mfma_f32_16x16x32_bf16 v[50:53], v[158:161], v[166:169], v[50:53]
	v_mfma_f32_16x16x32_bf16 v[38:41], v[150:153], v[174:177], v[38:41]
	v_mfma_f32_16x16x32_bf16 v[34:37], v[158:161], v[174:177], v[34:37]
	v_mfma_f32_16x16x32_bf16 v[22:25], v[150:153], v[182:185], v[22:25]
	v_mfma_f32_16x16x32_bf16 v[18:21], v[158:161], v[182:185], v[18:21]
	v_mfma_f32_16x16x32_bf16 v[6:9], v[150:153], v[190:193], v[6:9]
	v_mfma_f32_16x16x32_bf16 v[2:5], v[158:161], v[190:193], v[2:5]
	s_setprio 0
	s_barrier
	ds_read_b128 v[82:85], v246 offset:32768
	ds_read_b128 v[98:101], v246 offset:33792
	ds_read_b128 v[102:105], v246 offset:34816
	ds_read_b128 v[106:109], v246 offset:35840
	ds_read_b128 v[146:149], v246 offset:49152
	ds_read_b128 v[150:153], v246 offset:50176
	ds_read_b128 v[154:157], v246 offset:51200
	ds_read_b128 v[158:161], v246 offset:52224
	s_mov_b32 m0, s31
	ds_read_b128 v[162:165], v249 offset:32768
	ds_read_b128 v[166:169], v249 offset:33792
	ds_read_b128 v[170:173], v249 offset:34816
	ds_read_b128 v[174:177], v249 offset:35840
	ds_read_b128 v[178:181], v249 offset:36864
	ds_read_b128 v[182:185], v249 offset:37888
	ds_read_b128 v[186:189], v249 offset:38912
	global_load_lds_dwordx4 v224, s[20:21]
	s_mov_b32 m0, s33
	ds_read_b128 v[190:193], v249 offset:39936
	global_load_lds_dwordx4 v226, s[20:21]
	s_waitcnt vmcnt(8)
	s_waitcnt lgkmcnt(0)
	s_barrier
	s_setprio 1
	v_mfma_f32_16x16x32_bf16 v[142:145], v[82:85], v[162:165], v[142:145]
	v_mfma_f32_16x16x32_bf16 v[138:141], v[102:105], v[162:165], v[138:141]
	v_mfma_f32_16x16x32_bf16 v[126:129], v[82:85], v[170:173], v[126:129]
	v_mfma_f32_16x16x32_bf16 v[122:125], v[102:105], v[170:173], v[122:125]
	v_mfma_f32_16x16x32_bf16 v[110:113], v[82:85], v[178:181], v[110:113]
	v_mfma_f32_16x16x32_bf16 v[94:97], v[102:105], v[178:181], v[94:97]
	v_mfma_f32_16x16x32_bf16 v[78:81], v[82:85], v[186:189], v[78:81]
	v_mfma_f32_16x16x32_bf16 v[74:77], v[102:105], v[186:189], v[74:77]
	v_mfma_f32_16x16x32_bf16 v[142:145], v[98:101], v[166:169], v[142:145]
	v_mfma_f32_16x16x32_bf16 v[138:141], v[106:109], v[166:169], v[138:141]
	v_mfma_f32_16x16x32_bf16 v[126:129], v[98:101], v[174:177], v[126:129]
	v_mfma_f32_16x16x32_bf16 v[122:125], v[106:109], v[174:177], v[122:125]
	v_mfma_f32_16x16x32_bf16 v[110:113], v[98:101], v[182:185], v[110:113]
	v_mfma_f32_16x16x32_bf16 v[94:97], v[106:109], v[182:185], v[94:97]
	v_mfma_f32_16x16x32_bf16 v[78:81], v[98:101], v[190:193], v[78:81]
	v_mfma_f32_16x16x32_bf16 v[74:77], v[106:109], v[190:193], v[74:77]
	v_mfma_f32_16x16x32_bf16 v[134:137], v[146:149], v[162:165], v[134:137]
	v_mfma_f32_16x16x32_bf16 v[130:133], v[154:157], v[162:165], v[130:133]
	v_mfma_f32_16x16x32_bf16 v[118:121], v[146:149], v[170:173], v[118:121]
	v_mfma_f32_16x16x32_bf16 v[114:117], v[154:157], v[170:173], v[114:117]
	v_mfma_f32_16x16x32_bf16 v[90:93], v[146:149], v[178:181], v[90:93]
	v_mfma_f32_16x16x32_bf16 v[86:89], v[154:157], v[178:181], v[86:89]
	v_mfma_f32_16x16x32_bf16 v[70:73], v[146:149], v[186:189], v[70:73]
	v_mfma_f32_16x16x32_bf16 v[66:69], v[154:157], v[186:189], v[66:69]
	v_mfma_f32_16x16x32_bf16 v[134:137], v[150:153], v[166:169], v[134:137]
	v_mfma_f32_16x16x32_bf16 v[130:133], v[158:161], v[166:169], v[130:133]
	v_mfma_f32_16x16x32_bf16 v[118:121], v[150:153], v[174:177], v[118:121]
	v_mfma_f32_16x16x32_bf16 v[114:117], v[158:161], v[174:177], v[114:117]
	v_mfma_f32_16x16x32_bf16 v[90:93], v[150:153], v[182:185], v[90:93]
	v_mfma_f32_16x16x32_bf16 v[86:89], v[158:161], v[182:185], v[86:89]
	v_mfma_f32_16x16x32_bf16 v[70:73], v[150:153], v[190:193], v[70:73]
	v_mfma_f32_16x16x32_bf16 v[66:69], v[158:161], v[190:193], v[66:69]
	s_setprio 0
	s_barrier
; #define PG8_STAGE(bufoff, gbase, voff) do { _Pragma("unroll") for (int _i = 0; _i < 2; ++_i) \
;         __builtin_amdgcn_global_load_lds((const unsigned*)((const char*)(gbase) + (voff)[_i]), (PG8_LAS unsigned*)(lds + (bufoff) + ldsw + _i * 8192), 16, 0, 0); } while (0)
; #define PG8_LDA(dst, b, h) do { _Pragma("unroll") for (int m = 0; m < 4; ++m) _Pragma("unroll") for (int k = 0; k < 2; ++k) dst[m][k] = *(const PG8_LAS bf16x8*)(lds + PG8_SA(b, h) + aoff + m * 2048 + k * 1024); } while (0)
; #define PG8_MMA(ai, bj, At, Bt) do { __builtin_amdgcn_s_setprio(1); _Pragma("unroll") for (int m = 0; m < 4; ++m) _Pragma("unroll") for (int n = 0; n < 2; ++n) _Pragma("unroll") for (int k = 0; k < 2; ++k) \
;         acc[ai][bj][m][n] = __builtin_amdgcn_mfma_f32_16x16x32_bf16(Bt[n][k], At[m][k], acc[ai][bj][m][n], 0, 0, 0); __builtin_amdgcn_s_setprio(0); } while (0)
; #define PG8_WAIT_V(n) asm volatile("s_waitcnt vmcnt(" #n ")" ::: "memory")
; #define PG8_WAIT_L(n) asm volatile("s_waitcnt lgkmcnt(" #n ")" ::: "memory")
; #define PG8_BAR __builtin_amdgcn_s_barrier()
; #define PG8_SCHED __builtin_amdgcn_sched_barrier(0)
; template <class Epi, class Sched, bool ALIGN_EPI = false, bool SP2 = false>
; __device__ __forceinline__ void gemm_phase(PG8_LAS unsigned char* lds, const Gemm g, const Sched& S, const Epi& E) {
;     ...
;             PG8_LDA(At, 1, 1); PG8_STAGE(PG8_SB(1, 0), b3, voffB); PG8_STAGE(PG8_SB(1, 1), b3 + hstep, voffB); PG8_STAGE(PG8_SA(1, 0), a3, voffA);
;             PG8_WAIT_V(8); PG8_WAIT_L(0); PG8_BAR; PG8_MMA(1, 0, At, B0); PG8_MMA(1, 1, At, B1); PG8_BAR; PG8_SCHED;
	s_add_i32 m0, s22, 0x17f80
	ds_read_b128 v[162:165], v249 offset:49152
	ds_read_b128 v[166:169], v249 offset:50176
	ds_read_b128 v[170:173], v249 offset:51200
	global_load_lds_dwordx4 v[194:195], off offset:128
	s_add_i32 m0, s22, 0x19f80
	ds_read_b128 v[174:177], v249 offset:52224
	global_load_lds_dwordx4 v[196:197], off offset:128
	s_add_i32 m0, s22, 0x1bf80
	ds_read_b128 v[178:181], v249 offset:53248
	global_load_lds_dwordx4 v[198:199], off offset:128
	s_add_i32 m0, s22, 0x1df80
	ds_read_b128 v[182:185], v249 offset:54272
	global_load_lds_dwordx4 v[200:201], off offset:128
	s_sub_i32 m0, s39, 0x80
	ds_read_b128 v[186:189], v249 offset:55296
	global_load_lds_dwordx4 v[202:203], off offset:128
	s_sub_i32 m0, s65, 0x80
	ds_read_b128 v[190:193], v249 offset:56320
	global_load_lds_dwordx4 v[204:205], off offset:128
	s_waitcnt vmcnt(8)
	s_waitcnt lgkmcnt(0)
	s_barrier
	s_setprio 1
	v_mfma_f32_16x16x32_bf16 v[62:65], v[82:85], v[162:165], v[62:65]
	v_mfma_f32_16x16x32_bf16 v[58:61], v[102:105], v[162:165], v[58:61]
	v_mfma_f32_16x16x32_bf16 v[46:49], v[82:85], v[170:173], v[46:49]
	v_mfma_f32_16x16x32_bf16 v[42:45], v[102:105], v[170:173], v[42:45]
	v_mfma_f32_16x16x32_bf16 v[30:33], v[82:85], v[178:181], v[30:33]
	v_mfma_f32_16x16x32_bf16 v[26:29], v[102:105], v[178:181], v[26:29]
	v_mfma_f32_16x16x32_bf16 v[14:17], v[82:85], v[186:189], v[14:17]
	v_mfma_f32_16x16x32_bf16 v[10:13], v[102:105], v[186:189], v[10:13]
	v_mfma_f32_16x16x32_bf16 v[62:65], v[98:101], v[166:169], v[62:65]
	v_mfma_f32_16x16x32_bf16 v[58:61], v[106:109], v[166:169], v[58:61]
	v_mfma_f32_16x16x32_bf16 v[46:49], v[98:101], v[174:177], v[46:49]
	v_mfma_f32_16x16x32_bf16 v[42:45], v[106:109], v[174:177], v[42:45]
	v_mfma_f32_16x16x32_bf16 v[30:33], v[98:101], v[182:185], v[30:33]
	v_mfma_f32_16x16x32_bf16 v[26:29], v[106:109], v[182:185], v[26:29]
	v_mfma_f32_16x16x32_bf16 v[14:17], v[98:101], v[190:193], v[14:17]
	v_mfma_f32_16x16x32_bf16 v[10:13], v[106:109], v[190:193], v[10:13]
	v_mfma_f32_16x16x32_bf16 v[54:57], v[146:149], v[162:165], v[54:57]
	v_mfma_f32_16x16x32_bf16 v[50:53], v[154:157], v[162:165], v[50:53]
	v_mfma_f32_16x16x32_bf16 v[38:41], v[146:149], v[170:173], v[38:41]
	v_mfma_f32_16x16x32_bf16 v[34:37], v[154:157], v[170:173], v[34:37]
	v_mfma_f32_16x16x32_bf16 v[22:25], v[146:149], v[178:181], v[22:25]
	v_mfma_f32_16x16x32_bf16 v[18:21], v[154:157], v[178:181], v[18:21]
	v_mfma_f32_16x16x32_bf16 v[6:9], v[146:149], v[186:189], v[6:9]
	v_mfma_f32_16x16x32_bf16 v[2:5], v[154:157], v[186:189], v[2:5]
	v_mfma_f32_16x16x32_bf16 v[54:57], v[150:153], v[166:169], v[54:57]
	v_mfma_f32_16x16x32_bf16 v[50:53], v[158:161], v[166:169], v[50:53]
	v_mfma_f32_16x16x32_bf16 v[38:41], v[150:153], v[174:177], v[38:41]
	v_mfma_f32_16x16x32_bf16 v[34:37], v[158:161], v[174:177], v[34:37]
	v_mfma_f32_16x16x32_bf16 v[22:25], v[150:153], v[182:185], v[22:25]
	v_mfma_f32_16x16x32_bf16 v[18:21], v[158:161], v[182:185], v[18:21]
	v_mfma_f32_16x16x32_bf16 v[6:9], v[150:153], v[190:193], v[6:9]
	v_mfma_f32_16x16x32_bf16 v[2:5], v[158:161], v[190:193], v[2:5]
	s_setprio 0
	s_barrier
	s_add_u32 s10, s10, 0x100
	s_addc_u32 s11, s11, 0
	s_add_u32 s62, s62, 0x100
	s_addc_u32 s63, s63, 0
	s_cmp_ge_i32 s78, s67
	s_mov_b32 s20, s78
	s_cbranch_scc0 .LBB0_570

; #define PG8_STAGE(bufoff, gbase, voff) do { _Pragma("unroll") for (int _i = 0; _i < 2; ++_i) \
;         __builtin_amdgcn_global_load_lds((const unsigned*)((const char*)(gbase) + (voff)[_i]), (PG8_LAS unsigned*)(lds + (bufoff) + ldsw + _i * 8192), 16, 0, 0); } while (0)
; #define PG8_LDA(dst, b, h) do { _Pragma("unroll") for (int m = 0; m < 4; ++m) _Pragma("unroll") for (int k = 0; k < 2; ++k) dst[m][k] = *(const PG8_LAS bf16x8*)(lds + PG8_SA(b, h) + aoff + m * 2048 + k * 1024); } while (0)
; #define PG8_LDB(dst, b, h) do { _Pragma("unroll") for (int n = 0; n < 2; ++n) _Pragma("unroll") for (int k = 0; k < 2; ++k) dst[n][k] = *(const PG8_LAS bf16x8*)(lds + PG8_SB(b, h) + boff + n * 2048 + k * 1024); } while (0)
; #define PG8_MMA(ai, bj, At, Bt) do { __builtin_amdgcn_s_setprio(1); _Pragma("unroll") for (int m = 0; m < 4; ++m) _Pragma("unroll") for (int n = 0; n < 2; ++n) _Pragma("unroll") for (int k = 0; k < 2; ++k) \
;         acc[ai][bj][m][n] = __builtin_amdgcn_mfma_f32_16x16x32_bf16(Bt[n][k], At[m][k], acc[ai][bj][m][n], 0, 0, 0); __builtin_amdgcn_s_setprio(0); } while (0)
; #define PG8_WAIT_V(n) asm volatile("s_waitcnt vmcnt(" #n ")" ::: "memory")
; #define PG8_WAIT_L(n) asm volatile("s_waitcnt lgkmcnt(" #n ")" ::: "memory")
; #define PG8_BAR __builtin_amdgcn_s_barrier()
; #define PG8_SCHED __builtin_amdgcn_sched_barrier(0)
; template <class Epi, class Sched, bool ALIGN_EPI = false, bool SP2 = false>
; __device__ __forceinline__ void gemm_phase(PG8_LAS unsigned char* lds, const Gemm g, const Sched& S, const Epi& E) {
;     ...
;         for (int t = 0; t < nt; t += 2) {
;             const bool last = (t == nt - 2);
;             const char* a1 = cA + (size_t)(t + 1) * kstep;
;             const char* a2 = last ? nA : cA + (size_t)(t + 2) * kstep; const char* b2 = last ? nB : cB + (size_t)(t + 2) * kstep;
;             const char* a3 = a2 + kstep; const char* b3 = b2 + kstep;
;             if (last && has_next) S.a_ready(nxt);
;             if constexpr (SP2) {
;             PG8_LDB(B0, 0, 0); PG8_LDB(B1, 0, 1); PG8_SCHED; PG8_LDA(At, 0, 0); PG8_STAGE(PG8_SA(1, 1), a1 + hstep, voffA);
;             PG8_WAIT_V(8); PG8_WAIT_L(0); PG8_BAR; PG8_MMA(0, 0, At, B0); PG8_MMA(0, 1, At, B1); PG8_BAR; PG8_SCHED;
;             PG8_LDA(At, 0, 1); PG8_STAGE(PG8_SB(0, 0), b2, voffB); PG8_STAGE(PG8_SB(0, 1), b2 + hstep, voffB); PG8_STAGE(PG8_SA(0, 0), a2, voffA);
.LBB0_641:
	s_add_i32 s68, s20, 2
	s_add_u32 s69, s8, 0x80
	s_addc_u32 s21, s9, 0
	s_cmp_eq_u32 s63, s20
	s_cselect_b32 s21, s49, s21
	s_cselect_b32 s20, s48, s69
	s_cselect_b32 s71, s51, s53
	s_cselect_b32 s70, s50, s52
	ds_read_b128 v[130:133], v181
	ds_read_b128 v[134:137], v181 offset:1024
	ds_read_b128 v[138:141], v181 offset:2048
	ds_read_b128 v[142:145], v181 offset:3072
	ds_read_b128 v[146:149], v181 offset:16384
	ds_read_b128 v[150:153], v181 offset:17408
	ds_read_b128 v[166:169], v181 offset:18432
	ds_read_b128 v[170:173], v181 offset:19456
	s_add_i32 m0, s55, 0xc000
	ds_read_b128 v[174:177], v183
	ds_read_b128 v[184:187], v183 offset:1024
	ds_read_b128 v[188:191], v183 offset:2048
	ds_read_b128 v[192:195], v183 offset:3072
	ds_read_b128 v[196:199], v183 offset:4096
	ds_read_b128 v[200:203], v183 offset:5120
	ds_read_b128 v[204:207], v183 offset:6144
	global_load_lds_dwordx4 v162, s[8:9]
	s_add_i32 m0, s55, 0xe000
	ds_read_b128 v[208:211], v183 offset:7168
	global_load_lds_dwordx4 v164, s[8:9]
	s_waitcnt vmcnt(8)
	s_waitcnt lgkmcnt(0)
	s_barrier
	s_setprio 1
	v_mfma_f32_16x16x32_bf16 v[122:125], v[130:133], v[174:177], v[122:125]
	v_mfma_f32_16x16x32_bf16 v[118:121], v[138:141], v[174:177], v[118:121]
	v_mfma_f32_16x16x32_bf16 v[106:109], v[130:133], v[188:191], v[106:109]
	v_mfma_f32_16x16x32_bf16 v[102:105], v[138:141], v[188:191], v[102:105]
	v_mfma_f32_16x16x32_bf16 v[90:93], v[130:133], v[196:199], v[90:93]
	v_mfma_f32_16x16x32_bf16 v[86:89], v[138:141], v[196:199], v[86:89]
	v_mfma_f32_16x16x32_bf16 v[74:77], v[130:133], v[204:207], v[74:77]
	v_mfma_f32_16x16x32_bf16 v[70:73], v[138:141], v[204:207], v[70:73]
	v_mfma_f32_16x16x32_bf16 v[122:125], v[134:137], v[184:187], v[122:125]
	v_mfma_f32_16x16x32_bf16 v[118:121], v[142:145], v[184:187], v[118:121]
	v_mfma_f32_16x16x32_bf16 v[106:109], v[134:137], v[192:195], v[106:109]
	v_mfma_f32_16x16x32_bf16 v[102:105], v[142:145], v[192:195], v[102:105]
	v_mfma_f32_16x16x32_bf16 v[90:93], v[134:137], v[200:203], v[90:93]
	v_mfma_f32_16x16x32_bf16 v[86:89], v[142:145], v[200:203], v[86:89]
	v_mfma_f32_16x16x32_bf16 v[74:77], v[134:137], v[208:211], v[74:77]
	v_mfma_f32_16x16x32_bf16 v[70:73], v[142:145], v[208:211], v[70:73]
	v_mfma_f32_16x16x32_bf16 v[126:129], v[146:149], v[174:177], v[126:129]
	v_mfma_f32_16x16x32_bf16 v[114:117], v[166:169], v[174:177], v[114:117]
	v_mfma_f32_16x16x32_bf16 v[110:113], v[146:149], v[188:191], v[110:113]
	v_mfma_f32_16x16x32_bf16 v[98:101], v[166:169], v[188:191], v[98:101]
	v_mfma_f32_16x16x32_bf16 v[94:97], v[146:149], v[196:199], v[94:97]
	v_mfma_f32_16x16x32_bf16 v[82:85], v[166:169], v[196:199], v[82:85]
	v_mfma_f32_16x16x32_bf16 v[78:81], v[146:149], v[204:207], v[78:81]
	v_mfma_f32_16x16x32_bf16 v[66:69], v[166:169], v[204:207], v[66:69]
	v_mfma_f32_16x16x32_bf16 v[126:129], v[150:153], v[184:187], v[126:129]
	v_mfma_f32_16x16x32_bf16 v[114:117], v[170:173], v[184:187], v[114:117]
	v_mfma_f32_16x16x32_bf16 v[110:113], v[150:153], v[192:195], v[110:113]
	v_mfma_f32_16x16x32_bf16 v[98:101], v[170:173], v[192:195], v[98:101]
	v_mfma_f32_16x16x32_bf16 v[94:97], v[150:153], v[200:203], v[94:97]
	v_mfma_f32_16x16x32_bf16 v[82:85], v[170:173], v[200:203], v[82:85]
	v_mfma_f32_16x16x32_bf16 v[78:81], v[150:153], v[208:211], v[78:81]
	v_mfma_f32_16x16x32_bf16 v[66:69], v[170:173], v[208:211], v[66:69]
	s_setprio 0
	s_barrier
	v_lshl_add_u64 v[178:179], s[70:71], 0, v[0:1]
	s_add_i32 m0, s23, 0x10000
	ds_read_b128 v[174:177], v183 offset:16384
	ds_read_b128 v[184:187], v183 offset:17408
	ds_read_b128 v[188:191], v183 offset:18432
	ds_read_b128 v[192:195], v183 offset:19456
	ds_read_b128 v[196:199], v183 offset:20480
	ds_read_b128 v[200:203], v183 offset:21504
	ds_read_b128 v[204:207], v183 offset:22528
	ds_read_b128 v[208:211], v183 offset:23552
	global_load_lds_dwordx4 v[178:179], off
	s_add_i32 m0, s23, 0x12000
	v_lshl_add_u64 v[212:213], s[70:71], 0, v[154:155]
	s_add_u32 s70, s70, s10
	s_addc_u32 s71, s71, s11
	global_load_lds_dwordx4 v[212:213], off
	v_lshl_add_u64 v[214:215], s[70:71], 0, v[0:1]
	s_add_i32 m0, s23, 0x14000
	v_lshl_add_u64 v[218:219], s[70:71], 0, v[154:155]
	global_load_lds_dwordx4 v[214:215], off
	s_add_i32 m0, s23, 0x16000
	v_lshl_add_u64 v[220:221], s[20:21], 0, v[158:159]
	global_load_lds_dwordx4 v[218:219], off
	s_mov_b32 m0, s55
	v_lshl_add_u64 v[222:223], s[20:21], 0, v[156:157]
	global_load_lds_dwordx4 v[220:221], off
	s_mov_b32 m0, s56
	s_nop 0
	global_load_lds_dwordx4 v[222:223], off
	s_waitcnt vmcnt(8)
	s_waitcnt lgkmcnt(0)
	s_barrier
; #define PG8_STAGE(bufoff, gbase, voff) do { _Pragma("unroll") for (int _i = 0; _i < 2; ++_i) \
;         __builtin_amdgcn_global_load_lds((const unsigned*)((const char*)(gbase) + (voff)[_i]), (PG8_LAS unsigned*)(lds + (bufoff) + ldsw + _i * 8192), 16, 0, 0); } while (0)
; #define PG8_LDA(dst, b, h) do { _Pragma("unroll") for (int m = 0; m < 4; ++m) _Pragma("unroll") for (int k = 0; k < 2; ++k) dst[m][k] = *(const PG8_LAS bf16x8*)(lds + PG8_SA(b, h) + aoff + m * 2048 + k * 1024); } while (0)
; #define PG8_LDB(dst, b, h) do { _Pragma("unroll") for (int n = 0; n < 2; ++n) _Pragma("unroll") for (int k = 0; k < 2; ++k) dst[n][k] = *(const PG8_LAS bf16x8*)(lds + PG8_SB(b, h) + boff + n * 2048 + k * 1024); } while (0)
; #define PG8_MMA(ai, bj, At, Bt) do { __builtin_amdgcn_s_setprio(1); _Pragma("unroll") for (int m = 0; m < 4; ++m) _Pragma("unroll") for (int n = 0; n < 2; ++n) _Pragma("unroll") for (int k = 0; k < 2; ++k) \
;         acc[ai][bj][m][n] = __builtin_amdgcn_mfma_f32_16x16x32_bf16(Bt[n][k], At[m][k], acc[ai][bj][m][n], 0, 0, 0); __builtin_amdgcn_s_setprio(0); } while (0)
; #define PG8_WAIT_V(n) asm volatile("s_waitcnt vmcnt(" #n ")" ::: "memory")
; #define PG8_WAIT_L(n) asm volatile("s_waitcnt lgkmcnt(" #n ")" ::: "memory")
; #define PG8_BAR __builtin_amdgcn_s_barrier()
; #define PG8_SCHED __builtin_amdgcn_sched_barrier(0)
; template <class Epi, class Sched, bool ALIGN_EPI = false, bool SP2 = false>
; __device__ __forceinline__ void gemm_phase(PG8_LAS unsigned char* lds, const Gemm g, const Sched& S, const Epi& E) {
;     ...
;             PG8_WAIT_V(8); PG8_WAIT_L(0); PG8_BAR; PG8_MMA(1, 0, At, B0); PG8_MMA(1, 1, At, B1); PG8_BAR; PG8_SCHED;
;             PG8_LDB(B0, 1, 0); PG8_LDB(B1, 1, 1); PG8_SCHED; PG8_LDA(At, 1, 0); PG8_STAGE(PG8_SA(0, 1), a2 + hstep, voffA);
;             PG8_WAIT_V(8); PG8_WAIT_L(0); PG8_BAR; PG8_MMA(0, 0, At, B0); PG8_MMA(0, 1, At, B1); PG8_BAR; PG8_SCHED;
	s_setprio 1
	v_mfma_f32_16x16x32_bf16 v[58:61], v[130:133], v[174:177], v[58:61]
	v_mfma_f32_16x16x32_bf16 v[54:57], v[138:141], v[174:177], v[54:57]
	v_mfma_f32_16x16x32_bf16 v[42:45], v[130:133], v[188:191], v[42:45]
	v_mfma_f32_16x16x32_bf16 v[38:41], v[138:141], v[188:191], v[38:41]
	v_mfma_f32_16x16x32_bf16 v[26:29], v[130:133], v[196:199], v[26:29]
	v_mfma_f32_16x16x32_bf16 v[22:25], v[138:141], v[196:199], v[22:25]
	v_mfma_f32_16x16x32_bf16 v[10:13], v[130:133], v[204:207], v[10:13]
	v_mfma_f32_16x16x32_bf16 v[6:9], v[138:141], v[204:207], v[6:9]
	v_mfma_f32_16x16x32_bf16 v[58:61], v[134:137], v[184:187], v[58:61]
	v_mfma_f32_16x16x32_bf16 v[54:57], v[142:145], v[184:187], v[54:57]
	v_mfma_f32_16x16x32_bf16 v[42:45], v[134:137], v[192:195], v[42:45]
	v_mfma_f32_16x16x32_bf16 v[38:41], v[142:145], v[192:195], v[38:41]
	v_mfma_f32_16x16x32_bf16 v[26:29], v[134:137], v[200:203], v[26:29]
	v_mfma_f32_16x16x32_bf16 v[22:25], v[142:145], v[200:203], v[22:25]
	v_mfma_f32_16x16x32_bf16 v[10:13], v[134:137], v[208:211], v[10:13]
	v_mfma_f32_16x16x32_bf16 v[6:9], v[142:145], v[208:211], v[6:9]
	v_mfma_f32_16x16x32_bf16 v[62:65], v[146:149], v[174:177], v[62:65]
	v_mfma_f32_16x16x32_bf16 v[50:53], v[166:169], v[174:177], v[50:53]
	v_mfma_f32_16x16x32_bf16 v[46:49], v[146:149], v[188:191], v[46:49]
	v_mfma_f32_16x16x32_bf16 v[34:37], v[166:169], v[188:191], v[34:37]
	v_mfma_f32_16x16x32_bf16 v[30:33], v[146:149], v[196:199], v[30:33]
	v_mfma_f32_16x16x32_bf16 v[18:21], v[166:169], v[196:199], v[18:21]
	v_mfma_f32_16x16x32_bf16 v[14:17], v[146:149], v[204:207], v[14:17]
	v_mfma_f32_16x16x32_bf16 v[2:5], v[166:169], v[204:207], v[2:5]
	v_mfma_f32_16x16x32_bf16 v[62:65], v[150:153], v[184:187], v[62:65]
	v_mfma_f32_16x16x32_bf16 v[50:53], v[170:173], v[184:187], v[50:53]
	v_mfma_f32_16x16x32_bf16 v[46:49], v[150:153], v[192:195], v[46:49]
	v_mfma_f32_16x16x32_bf16 v[34:37], v[170:173], v[192:195], v[34:37]
	v_mfma_f32_16x16x32_bf16 v[30:33], v[150:153], v[200:203], v[30:33]
	v_mfma_f32_16x16x32_bf16 v[18:21], v[170:173], v[200:203], v[18:21]
	v_mfma_f32_16x16x32_bf16 v[14:17], v[150:153], v[208:211], v[14:17]
	v_mfma_f32_16x16x32_bf16 v[2:5], v[170:173], v[208:211], v[2:5]
	s_setprio 0
	s_barrier
	ds_read_b128 v[130:133], v181 offset:32768
	ds_read_b128 v[134:137], v181 offset:33792
	ds_read_b128 v[138:141], v181 offset:34816
	ds_read_b128 v[142:145], v181 offset:35840
	ds_read_b128 v[146:149], v181 offset:49152
	ds_read_b128 v[150:153], v181 offset:50176
	ds_read_b128 v[166:169], v181 offset:51200
	ds_read_b128 v[170:173], v181 offset:52224
	s_mov_b32 m0, s57
	ds_read_b128 v[174:177], v183 offset:32768
	ds_read_b128 v[184:187], v183 offset:33792
	ds_read_b128 v[188:191], v183 offset:34816
	ds_read_b128 v[192:195], v183 offset:35840
	ds_read_b128 v[196:199], v183 offset:36864
	ds_read_b128 v[200:203], v183 offset:37888
	ds_read_b128 v[204:207], v183 offset:38912
	global_load_lds_dwordx4 v162, s[20:21]
	s_mov_b32 m0, s58
	ds_read_b128 v[208:211], v183 offset:39936
	global_load_lds_dwordx4 v164, s[20:21]
	s_waitcnt vmcnt(8)
	s_waitcnt lgkmcnt(0)
	s_barrier
	s_setprio 1
	v_mfma_f32_16x16x32_bf16 v[122:125], v[130:133], v[174:177], v[122:125]
	v_mfma_f32_16x16x32_bf16 v[118:121], v[138:141], v[174:177], v[118:121]
	v_mfma_f32_16x16x32_bf16 v[106:109], v[130:133], v[188:191], v[106:109]
	v_mfma_f32_16x16x32_bf16 v[102:105], v[138:141], v[188:191], v[102:105]
	v_mfma_f32_16x16x32_bf16 v[90:93], v[130:133], v[196:199], v[90:93]
	v_mfma_f32_16x16x32_bf16 v[86:89], v[138:141], v[196:199], v[86:89]
	v_mfma_f32_16x16x32_bf16 v[74:77], v[130:133], v[204:207], v[74:77]
	v_mfma_f32_16x16x32_bf16 v[70:73], v[138:141], v[204:207], v[70:73]
	v_mfma_f32_16x16x32_bf16 v[122:125], v[134:137], v[184:187], v[122:125]
	v_mfma_f32_16x16x32_bf16 v[118:121], v[142:145], v[184:187], v[118:121]
	v_mfma_f32_16x16x32_bf16 v[106:109], v[134:137], v[192:195], v[106:109]
	v_mfma_f32_16x16x32_bf16 v[102:105], v[142:145], v[192:195], v[102:105]
	v_mfma_f32_16x16x32_bf16 v[90:93], v[134:137], v[200:203], v[90:93]
	v_mfma_f32_16x16x32_bf16 v[86:89], v[142:145], v[200:203], v[86:89]
	v_mfma_f32_16x16x32_bf16 v[74:77], v[134:137], v[208:211], v[74:77]
	v_mfma_f32_16x16x32_bf16 v[70:73], v[142:145], v[208:211], v[70:73]
	v_mfma_f32_16x16x32_bf16 v[126:129], v[146:149], v[174:177], v[126:129]
	v_mfma_f32_16x16x32_bf16 v[114:117], v[166:169], v[174:177], v[114:117]
	v_mfma_f32_16x16x32_bf16 v[110:113], v[146:149], v[188:191], v[110:113]
	v_mfma_f32_16x16x32_bf16 v[98:101], v[166:169], v[188:191], v[98:101]
	v_mfma_f32_16x16x32_bf16 v[94:97], v[146:149], v[196:199], v[94:97]
	v_mfma_f32_16x16x32_bf16 v[82:85], v[166:169], v[196:199], v[82:85]
	v_mfma_f32_16x16x32_bf16 v[78:81], v[146:149], v[204:207], v[78:81]
	v_mfma_f32_16x16x32_bf16 v[66:69], v[166:169], v[204:207], v[66:69]
	v_mfma_f32_16x16x32_bf16 v[126:129], v[150:153], v[184:187], v[126:129]
	v_mfma_f32_16x16x32_bf16 v[114:117], v[170:173], v[184:187], v[114:117]
	v_mfma_f32_16x16x32_bf16 v[110:113], v[150:153], v[192:195], v[110:113]
	v_mfma_f32_16x16x32_bf16 v[98:101], v[170:173], v[192:195], v[98:101]
	v_mfma_f32_16x16x32_bf16 v[94:97], v[150:153], v[200:203], v[94:97]
	v_mfma_f32_16x16x32_bf16 v[82:85], v[170:173], v[200:203], v[82:85]
	v_mfma_f32_16x16x32_bf16 v[78:81], v[150:153], v[208:211], v[78:81]
	v_mfma_f32_16x16x32_bf16 v[66:69], v[170:173], v[208:211], v[66:69]
	s_setprio 0
	s_barrier
; #define PG8_STAGE(bufoff, gbase, voff) do { _Pragma("unroll") for (int _i = 0; _i < 2; ++_i) \
;         __builtin_amdgcn_global_load_lds((const unsigned*)((const char*)(gbase) + (voff)[_i]), (PG8_LAS unsigned*)(lds + (bufoff) + ldsw + _i * 8192), 16, 0, 0); } while (0)
; #define PG8_LDA(dst, b, h) do { _Pragma("unroll") for (int m = 0; m < 4; ++m) _Pragma("unroll") for (int k = 0; k < 2; ++k) dst[m][k] = *(const PG8_LAS bf16x8*)(lds + PG8_SA(b, h) + aoff + m * 2048 + k * 1024); } while (0)
; #define PG8_MMA(ai, bj, At, Bt) do { __builtin_amdgcn_s_setprio(1); _Pragma("unroll") for (int m = 0; m < 4; ++m) _Pragma("unroll") for (int n = 0; n < 2; ++n) _Pragma("unroll") for (int k = 0; k < 2; ++k) \
;         acc[ai][bj][m][n] = __builtin_amdgcn_mfma_f32_16x16x32_bf16(Bt[n][k], At[m][k], acc[ai][bj][m][n], 0, 0, 0); __builtin_amdgcn_s_setprio(0); } while (0)
; #define PG8_WAIT_V(n) asm volatile("s_waitcnt vmcnt(" #n ")" ::: "memory")
; #define PG8_WAIT_L(n) asm volatile("s_waitcnt lgkmcnt(" #n ")" ::: "memory")
; #define PG8_BAR __builtin_amdgcn_s_barrier()
; #define PG8_SCHED __builtin_amdgcn_sched_barrier(0)
; template <class Epi, class Sched, bool ALIGN_EPI = false, bool SP2 = false>
; __device__ __forceinline__ void gemm_phase(PG8_LAS unsigned char* lds, const Gemm g, const Sched& S, const Epi& E) {
;     ...
;             PG8_LDA(At, 1, 1); PG8_STAGE(PG8_SB(1, 0), b3, voffB); PG8_STAGE(PG8_SB(1, 1), b3 + hstep, voffB); PG8_STAGE(PG8_SA(1, 0), a3, voffA);
;             PG8_WAIT_V(8); PG8_WAIT_L(0); PG8_BAR; PG8_MMA(1, 0, At, B0); PG8_MMA(1, 1, At, B1); PG8_BAR; PG8_SCHED;
	s_add_i32 m0, s23, 0x17f80
	ds_read_b128 v[174:177], v183 offset:49152
	ds_read_b128 v[184:187], v183 offset:50176
	ds_read_b128 v[188:191], v183 offset:51200
	global_load_lds_dwordx4 v[178:179], off offset:128
	s_add_i32 m0, s23, 0x19f80
	ds_read_b128 v[192:195], v183 offset:52224
	global_load_lds_dwordx4 v[212:213], off offset:128
	s_add_i32 m0, s23, 0x1bf80
	ds_read_b128 v[196:199], v183 offset:53248
	global_load_lds_dwordx4 v[214:215], off offset:128
	s_add_i32 m0, s23, 0x1df80
	ds_read_b128 v[200:203], v183 offset:54272
	global_load_lds_dwordx4 v[218:219], off offset:128
	s_sub_i32 m0, s59, 0x80
	ds_read_b128 v[204:207], v183 offset:55296
	global_load_lds_dwordx4 v[220:221], off offset:128
	s_sub_i32 m0, s60, 0x80
	ds_read_b128 v[208:211], v183 offset:56320
	global_load_lds_dwordx4 v[222:223], off offset:128
	s_waitcnt vmcnt(8)
	s_waitcnt lgkmcnt(0)
	s_barrier
	s_setprio 1
	v_mfma_f32_16x16x32_bf16 v[58:61], v[130:133], v[174:177], v[58:61]
	v_mfma_f32_16x16x32_bf16 v[54:57], v[138:141], v[174:177], v[54:57]
	v_mfma_f32_16x16x32_bf16 v[42:45], v[130:133], v[188:191], v[42:45]
	v_mfma_f32_16x16x32_bf16 v[38:41], v[138:141], v[188:191], v[38:41]
	v_mfma_f32_16x16x32_bf16 v[26:29], v[130:133], v[196:199], v[26:29]
	v_mfma_f32_16x16x32_bf16 v[22:25], v[138:141], v[196:199], v[22:25]
	v_mfma_f32_16x16x32_bf16 v[10:13], v[130:133], v[204:207], v[10:13]
	v_mfma_f32_16x16x32_bf16 v[6:9], v[138:141], v[204:207], v[6:9]
	v_mfma_f32_16x16x32_bf16 v[58:61], v[134:137], v[184:187], v[58:61]
	v_mfma_f32_16x16x32_bf16 v[54:57], v[142:145], v[184:187], v[54:57]
	v_mfma_f32_16x16x32_bf16 v[42:45], v[134:137], v[192:195], v[42:45]
	v_mfma_f32_16x16x32_bf16 v[38:41], v[142:145], v[192:195], v[38:41]
	v_mfma_f32_16x16x32_bf16 v[26:29], v[134:137], v[200:203], v[26:29]
	v_mfma_f32_16x16x32_bf16 v[22:25], v[142:145], v[200:203], v[22:25]
	v_mfma_f32_16x16x32_bf16 v[10:13], v[134:137], v[208:211], v[10:13]
	v_mfma_f32_16x16x32_bf16 v[6:9], v[142:145], v[208:211], v[6:9]
	v_mfma_f32_16x16x32_bf16 v[62:65], v[146:149], v[174:177], v[62:65]
	v_mfma_f32_16x16x32_bf16 v[50:53], v[166:169], v[174:177], v[50:53]
	v_mfma_f32_16x16x32_bf16 v[46:49], v[146:149], v[188:191], v[46:49]
	v_mfma_f32_16x16x32_bf16 v[34:37], v[166:169], v[188:191], v[34:37]
	v_mfma_f32_16x16x32_bf16 v[30:33], v[146:149], v[196:199], v[30:33]
	v_mfma_f32_16x16x32_bf16 v[18:21], v[166:169], v[196:199], v[18:21]
	v_mfma_f32_16x16x32_bf16 v[14:17], v[146:149], v[204:207], v[14:17]
	v_mfma_f32_16x16x32_bf16 v[2:5], v[166:169], v[204:207], v[2:5]
	v_mfma_f32_16x16x32_bf16 v[62:65], v[150:153], v[184:187], v[62:65]
	v_mfma_f32_16x16x32_bf16 v[50:53], v[170:173], v[184:187], v[50:53]
	v_mfma_f32_16x16x32_bf16 v[46:49], v[150:153], v[192:195], v[46:49]
	v_mfma_f32_16x16x32_bf16 v[34:37], v[170:173], v[192:195], v[34:37]
	v_mfma_f32_16x16x32_bf16 v[30:33], v[150:153], v[200:203], v[30:33]
	v_mfma_f32_16x16x32_bf16 v[18:21], v[170:173], v[200:203], v[18:21]
	v_mfma_f32_16x16x32_bf16 v[14:17], v[150:153], v[208:211], v[14:17]
	v_mfma_f32_16x16x32_bf16 v[2:5], v[170:173], v[208:211], v[2:5]
	s_setprio 0
	s_barrier
	s_add_u32 s8, s8, 0x100
	s_addc_u32 s9, s9, 0
	s_add_u32 s52, s52, 0x100
	s_addc_u32 s53, s53, 0
	s_cmp_ge_i32 s68, s62
	s_mov_b32 s20, s68
	s_cbranch_scc0 .LBB0_641
